# all GEMM K-loops MFMA order variant m_nb (A fragment held for 8 MFMAs; B0/B1 alternate; accumulate chains)
# speedup vs baseline: 1.0002x; 1.0002x over previous
; #define PG8_STAGE(bufoff, gbase, voff) do { _Pragma("unroll") for (int _i = 0; _i < 2; ++_i) \
;         __builtin_amdgcn_global_load_lds((const unsigned*)((const char*)(gbase) + (voff)[_i]), (PG8_LAS unsigned*)(lds + (bufoff) + ldsw + _i * 8192), 16, 0, 0); } while (0)
; #define PG8_LDA(dst, b, h) do { _Pragma("unroll") for (int m = 0; m < 4; ++m) _Pragma("unroll") for (int k = 0; k < 2; ++k) dst[m][k] = *(const PG8_LAS bf16x8*)(lds + PG8_SA(b, h) + aoff + m * 2048 + k * 1024); } while (0)
; #define PG8_LDB(dst, b, h) do { _Pragma("unroll") for (int n = 0; n < 2; ++n) _Pragma("unroll") for (int k = 0; k < 2; ++k) dst[n][k] = *(const PG8_LAS bf16x8*)(lds + PG8_SB(b, h) + boff + n * 2048 + k * 1024); } while (0)
; #define PG8_MMA(ai, bj, At, Bt) do { __builtin_amdgcn_s_setprio(1); _Pragma("unroll") for (int m = 0; m < 4; ++m) _Pragma("unroll") for (int n = 0; n < 2; ++n) _Pragma("unroll") for (int k = 0; k < 2; ++k) \
;         acc[ai][bj][m][n] = __builtin_amdgcn_mfma_f32_16x16x32_bf16(Bt[n][k], At[m][k], acc[ai][bj][m][n], 0, 0, 0); __builtin_amdgcn_s_setprio(0); } while (0)
; #define PG8_WAIT_V(n) asm volatile("s_waitcnt vmcnt(" #n ")" ::: "memory")
; #define PG8_WAIT_L(n) asm volatile("s_waitcnt lgkmcnt(" #n ")" ::: "memory")
; template <class Epi, class Sched, bool ALIGN_EPI = false, bool SP2 = false>
; __device__ __forceinline__ void gemm_phase(PG8_LAS unsigned char* lds, const Gemm g, const Sched& S, const Epi& E) {
;     ...
;             const bool last = (t == nt - 2);
;             const char* a1 = cA + (size_t)(t + 1) * kstep;
;             const char* a2 = last ? nA : cA + (size_t)(t + 2) * kstep; const char* b2 = last ? nB : cB + (size_t)(t + 2) * kstep;
;             const char* a3 = a2 + kstep; const char* b3 = b2 + kstep;
;             if (last && has_next) S.a_ready(nxt);
;             if constexpr (SP2) {
;             PG8_LDB(B0, 0, 0); PG8_LDB(B1, 0, 1); PG8_SCHED; PG8_LDA(At, 0, 0); PG8_STAGE(PG8_SA(1, 1), a1 + hstep, voffA);
;             PG8_WAIT_V(8); PG8_WAIT_L(0); PG8_BAR; PG8_MMA(0, 0, At, B0); PG8_MMA(0, 1, At, B1); PG8_BAR; PG8_SCHED;
;             PG8_LDA(At, 0, 1); PG8_STAGE(PG8_SB(0, 0), b2, voffB); PG8_STAGE(PG8_SB(0, 1), b2 + hstep, voffB); PG8_STAGE(PG8_SA(0, 0), a2, voffA);
;             PG8_WAIT_V(8); PG8_WAIT_L(0); PG8_BAR; PG8_MMA(1, 0, At, B0); PG8_MMA(1, 1, At, B1); PG8_BAR; PG8_SCHED;
.LBB11_228:
	ds_read_b128 v[152:155], v149
	ds_read_b128 v[156:159], v149 offset:1024
	ds_read_b128 v[160:163], v149 offset:2048
	ds_read_b128 v[164:167], v149 offset:3072
	ds_read_b128 v[168:171], v150
	ds_read_b128 v[172:175], v150 offset:1024
	ds_read_b128 v[176:179], v150 offset:2048
	ds_read_b128 v[180:183], v150 offset:3072
	s_add_u32 s30, s28, 0xfff80080
	s_addc_u32 s31, s29, -1
	s_cmp_eq_u32 s61, 28
	s_cselect_b32 s35, s21, s31
	s_cselect_b32 s34, s57, s30
	s_cselect_b32 s31, s19, s60
	s_cselect_b32 s30, s58, s59
	v_lshl_add_u64 v[144:145], s[28:29], 0, v[140:141]
	s_add_i32 m0, s27, 0xc000
	ds_read_b128 v[184:187], v151
	ds_read_b128 v[188:191], v151 offset:1024
	ds_read_b128 v[192:195], v151 offset:2048
	ds_read_b128 v[196:199], v151 offset:3072
	ds_read_b128 v[200:203], v151 offset:4096
	ds_read_b128 v[204:207], v151 offset:5120
	ds_read_b128 v[210:213], v151 offset:6144
	ds_read_b128 v[214:217], v151 offset:7168
	global_load_lds_dwordx4 v[144:145], off
	v_lshl_add_u64 v[144:145], s[28:29], 0, v[142:143]
	s_add_i32 m0, s27, 0xe000
	s_nop 0
	global_load_lds_dwordx4 v[144:145], off
	s_waitcnt vmcnt(8)
	s_waitcnt lgkmcnt(0)
	s_barrier
	s_setprio 1
	s_waitcnt lgkmcnt(0)
	v_mfma_f32_16x16x32_bf16 v[126:129], v[152:155], v[184:187], v[126:129]
	v_mfma_f32_16x16x32_bf16 v[126:129], v[156:159], v[188:191], v[126:129]
	v_mfma_f32_16x16x32_bf16 v[114:117], v[168:171], v[184:187], v[114:117]
	v_mfma_f32_16x16x32_bf16 v[114:117], v[172:175], v[188:191], v[114:117]
	v_mfma_f32_16x16x32_bf16 v[122:125], v[160:163], v[184:187], v[122:125]
	v_mfma_f32_16x16x32_bf16 v[122:125], v[164:167], v[188:191], v[122:125]
	v_mfma_f32_16x16x32_bf16 v[106:109], v[176:179], v[184:187], v[106:109]
	v_mfma_f32_16x16x32_bf16 v[106:109], v[180:183], v[188:191], v[106:109]
	v_mfma_f32_16x16x32_bf16 v[118:121], v[152:155], v[192:195], v[118:121]
	v_mfma_f32_16x16x32_bf16 v[118:121], v[156:159], v[196:199], v[118:121]
	v_mfma_f32_16x16x32_bf16 v[98:101], v[168:171], v[192:195], v[98:101]
	v_mfma_f32_16x16x32_bf16 v[98:101], v[172:175], v[196:199], v[98:101]
	v_mfma_f32_16x16x32_bf16 v[110:113], v[160:163], v[192:195], v[110:113]
	v_mfma_f32_16x16x32_bf16 v[110:113], v[164:167], v[196:199], v[110:113]
	v_mfma_f32_16x16x32_bf16 v[90:93], v[176:179], v[192:195], v[90:93]
	v_mfma_f32_16x16x32_bf16 v[90:93], v[180:183], v[196:199], v[90:93]
	s_setprio 0
	s_setprio 1
	v_mfma_f32_16x16x32_bf16 v[102:105], v[152:155], v[200:203], v[102:105]
	v_mfma_f32_16x16x32_bf16 v[102:105], v[156:159], v[204:207], v[102:105]
	v_mfma_f32_16x16x32_bf16 v[82:85], v[168:171], v[200:203], v[82:85]
	v_mfma_f32_16x16x32_bf16 v[82:85], v[172:175], v[204:207], v[82:85]
	v_mfma_f32_16x16x32_bf16 v[94:97], v[160:163], v[200:203], v[94:97]
	v_mfma_f32_16x16x32_bf16 v[94:97], v[164:167], v[204:207], v[94:97]
	v_mfma_f32_16x16x32_bf16 v[74:77], v[176:179], v[200:203], v[74:77]
	v_mfma_f32_16x16x32_bf16 v[74:77], v[180:183], v[204:207], v[74:77]
	v_mfma_f32_16x16x32_bf16 v[86:89], v[152:155], v[210:213], v[86:89]
	v_mfma_f32_16x16x32_bf16 v[86:89], v[156:159], v[214:217], v[86:89]
	v_mfma_f32_16x16x32_bf16 v[70:73], v[168:171], v[210:213], v[70:73]
	v_mfma_f32_16x16x32_bf16 v[70:73], v[172:175], v[214:217], v[70:73]
	v_mfma_f32_16x16x32_bf16 v[78:81], v[160:163], v[210:213], v[78:81]
	v_mfma_f32_16x16x32_bf16 v[78:81], v[164:167], v[214:217], v[78:81]
	v_mfma_f32_16x16x32_bf16 v[66:69], v[176:179], v[210:213], v[66:69]
	v_mfma_f32_16x16x32_bf16 v[66:69], v[180:183], v[214:217], v[66:69]
	s_setprio 0
	s_barrier
	s_add_i32 s62, s50, s37
	v_lshl_add_u64 v[144:145], s[30:31], 0, v[134:135]
	s_mov_b32 m0, s62
	ds_read_b128 v[184:187], v151 offset:16384
	ds_read_b128 v[188:191], v151 offset:17408
	ds_read_b128 v[192:195], v151 offset:18432
	ds_read_b128 v[196:199], v151 offset:19456
	ds_read_b128 v[200:203], v151 offset:20480
	ds_read_b128 v[204:207], v151 offset:21504
	ds_read_b128 v[210:213], v151 offset:22528
	ds_read_b128 v[214:217], v151 offset:23552
	global_load_lds_dwordx4 v[144:145], off
	s_add_i32 m0, s62, 0x2000
	s_add_u32 s62, s30, 0x80000
	v_lshl_add_u64 v[218:219], s[30:31], 0, v[130:131]
	s_addc_u32 s63, s31, 0
	s_add_i32 s64, s51, s37
	global_load_lds_dwordx4 v[218:219], off
	v_lshl_add_u64 v[220:221], s[62:63], 0, v[134:135]
	s_mov_b32 m0, s64
	v_lshl_add_u64 v[222:223], s[34:35], 0, v[132:133]
	global_load_lds_dwordx4 v[220:221], off
	v_lshl_add_u64 v[220:221], s[62:63], 0, v[130:131]
	s_add_i32 m0, s64, 0x2000
	s_nop 0
	global_load_lds_dwordx4 v[220:221], off
	v_lshl_add_u64 v[220:221], s[34:35], 0, v[136:137]
	s_mov_b32 m0, s27
	s_nop 0
	global_load_lds_dwordx4 v[220:221], off
	s_mov_b32 m0, s39
	s_nop 0
	global_load_lds_dwordx4 v[222:223], off
	s_waitcnt vmcnt(8)
	s_waitcnt lgkmcnt(0)
	s_barrier
; #define PG8_STAGE(bufoff, gbase, voff) do { _Pragma("unroll") for (int _i = 0; _i < 2; ++_i) \
;         __builtin_amdgcn_global_load_lds((const unsigned*)((const char*)(gbase) + (voff)[_i]), (PG8_LAS unsigned*)(lds + (bufoff) + ldsw + _i * 8192), 16, 0, 0); } while (0)
; #define PG8_LDA(dst, b, h) do { _Pragma("unroll") for (int m = 0; m < 4; ++m) _Pragma("unroll") for (int k = 0; k < 2; ++k) dst[m][k] = *(const PG8_LAS bf16x8*)(lds + PG8_SA(b, h) + aoff + m * 2048 + k * 1024); } while (0)
; #define PG8_LDB(dst, b, h) do { _Pragma("unroll") for (int n = 0; n < 2; ++n) _Pragma("unroll") for (int k = 0; k < 2; ++k) dst[n][k] = *(const PG8_LAS bf16x8*)(lds + PG8_SB(b, h) + boff + n * 2048 + k * 1024); } while (0)
; #define PG8_MMA(ai, bj, At, Bt) do { __builtin_amdgcn_s_setprio(1); _Pragma("unroll") for (int m = 0; m < 4; ++m) _Pragma("unroll") for (int n = 0; n < 2; ++n) _Pragma("unroll") for (int k = 0; k < 2; ++k) \
;         acc[ai][bj][m][n] = __builtin_amdgcn_mfma_f32_16x16x32_bf16(Bt[n][k], At[m][k], acc[ai][bj][m][n], 0, 0, 0); __builtin_amdgcn_s_setprio(0); } while (0)
; #define PG8_WAIT_V(n) asm volatile("s_waitcnt vmcnt(" #n ")" ::: "memory")
; #define PG8_WAIT_L(n) asm volatile("s_waitcnt lgkmcnt(" #n ")" ::: "memory")
; #define PG8_BAR __builtin_amdgcn_s_barrier()
; #define PG8_SCHED __builtin_amdgcn_sched_barrier(0)
; template <class Epi, class Sched, bool ALIGN_EPI = false, bool SP2 = false>
; __device__ __forceinline__ void gemm_phase(PG8_LAS unsigned char* lds, const Gemm g, const Sched& S, const Epi& E) {
;     ...
;             PG8_WAIT_V(8); PG8_WAIT_L(0); PG8_BAR; PG8_MMA(1, 0, At, B0); PG8_MMA(1, 1, At, B1); PG8_BAR; PG8_SCHED;
;             PG8_LDB(B0, 1, 0); PG8_LDB(B1, 1, 1); PG8_SCHED; PG8_LDA(At, 1, 0); PG8_STAGE(PG8_SA(0, 1), a2 + hstep, voffA);
;             PG8_WAIT_V(8); PG8_WAIT_L(0); PG8_BAR; PG8_MMA(0, 0, At, B0); PG8_MMA(0, 1, At, B1); PG8_BAR; PG8_SCHED;
	s_setprio 1
	s_waitcnt lgkmcnt(0)
	v_mfma_f32_16x16x32_bf16 v[62:65], v[152:155], v[184:187], v[62:65]
	v_mfma_f32_16x16x32_bf16 v[62:65], v[156:159], v[188:191], v[62:65]
	v_mfma_f32_16x16x32_bf16 v[50:53], v[168:171], v[184:187], v[50:53]
	v_mfma_f32_16x16x32_bf16 v[50:53], v[172:175], v[188:191], v[50:53]
	v_mfma_f32_16x16x32_bf16 v[58:61], v[160:163], v[184:187], v[58:61]
	v_mfma_f32_16x16x32_bf16 v[58:61], v[164:167], v[188:191], v[58:61]
	v_mfma_f32_16x16x32_bf16 v[42:45], v[176:179], v[184:187], v[42:45]
	v_mfma_f32_16x16x32_bf16 v[42:45], v[180:183], v[188:191], v[42:45]
	v_mfma_f32_16x16x32_bf16 v[54:57], v[152:155], v[192:195], v[54:57]
	v_mfma_f32_16x16x32_bf16 v[54:57], v[156:159], v[196:199], v[54:57]
	v_mfma_f32_16x16x32_bf16 v[34:37], v[168:171], v[192:195], v[34:37]
	v_mfma_f32_16x16x32_bf16 v[34:37], v[172:175], v[196:199], v[34:37]
	v_mfma_f32_16x16x32_bf16 v[46:49], v[160:163], v[192:195], v[46:49]
	v_mfma_f32_16x16x32_bf16 v[46:49], v[164:167], v[196:199], v[46:49]
	v_mfma_f32_16x16x32_bf16 v[26:29], v[176:179], v[192:195], v[26:29]
	v_mfma_f32_16x16x32_bf16 v[26:29], v[180:183], v[196:199], v[26:29]
	s_setprio 0
	s_setprio 1
	v_mfma_f32_16x16x32_bf16 v[38:41], v[152:155], v[200:203], v[38:41]
	v_mfma_f32_16x16x32_bf16 v[38:41], v[156:159], v[204:207], v[38:41]
	v_mfma_f32_16x16x32_bf16 v[18:21], v[168:171], v[200:203], v[18:21]
	v_mfma_f32_16x16x32_bf16 v[18:21], v[172:175], v[204:207], v[18:21]
	v_mfma_f32_16x16x32_bf16 v[30:33], v[160:163], v[200:203], v[30:33]
	v_mfma_f32_16x16x32_bf16 v[30:33], v[164:167], v[204:207], v[30:33]
	v_mfma_f32_16x16x32_bf16 v[10:13], v[176:179], v[200:203], v[10:13]
	v_mfma_f32_16x16x32_bf16 v[10:13], v[180:183], v[204:207], v[10:13]
	v_mfma_f32_16x16x32_bf16 v[22:25], v[152:155], v[210:213], v[22:25]
	v_mfma_f32_16x16x32_bf16 v[22:25], v[156:159], v[214:217], v[22:25]
	v_mfma_f32_16x16x32_bf16 v[6:9], v[168:171], v[210:213], v[6:9]
	v_mfma_f32_16x16x32_bf16 v[6:9], v[172:175], v[214:217], v[6:9]
	v_mfma_f32_16x16x32_bf16 v[14:17], v[160:163], v[210:213], v[14:17]
	v_mfma_f32_16x16x32_bf16 v[14:17], v[164:167], v[214:217], v[14:17]
	v_mfma_f32_16x16x32_bf16 v[2:5], v[176:179], v[210:213], v[2:5]
	v_mfma_f32_16x16x32_bf16 v[2:5], v[180:183], v[214:217], v[2:5]
	s_setprio 0
	s_barrier
	s_add_i32 s62, 0, 0x18000
	s_add_i32 s63, 0, 0x1c000
	v_add_u32_e32 v164, s62, v147
	v_add_u32_e32 v180, s63, v147
	ds_read_b128 v[152:155], v164
	ds_read_b128 v[156:159], v164 offset:1024
	ds_read_b128 v[160:163], v164 offset:2048
	ds_read_b128 v[164:167], v164 offset:3072
	ds_read_b128 v[168:171], v180
	ds_read_b128 v[172:175], v180 offset:1024
	ds_read_b128 v[176:179], v180 offset:2048
	ds_read_b128 v[180:183], v180 offset:3072
	s_add_u32 s34, s34, 0x80000
	s_addc_u32 s35, s35, 0
	s_mov_b32 m0, s40
	v_lshl_add_u64 v[224:225], s[34:35], 0, v[136:137]
	ds_read_b128 v[184:187], v151 offset:32768
	ds_read_b128 v[188:191], v151 offset:33792
	ds_read_b128 v[192:195], v151 offset:34816
	ds_read_b128 v[196:199], v151 offset:35840
	ds_read_b128 v[200:203], v151 offset:36864
	ds_read_b128 v[204:207], v151 offset:37888
	ds_read_b128 v[210:213], v151 offset:38912
	ds_read_b128 v[214:217], v151 offset:39936
	global_load_lds_dwordx4 v[224:225], off
	v_lshl_add_u64 v[224:225], s[34:35], 0, v[132:133]
	s_mov_b32 m0, s41
	s_nop 0
	global_load_lds_dwordx4 v[224:225], off
	s_waitcnt vmcnt(8)
	s_waitcnt lgkmcnt(0)
	s_barrier
	s_setprio 1
	s_waitcnt lgkmcnt(0)
	v_mfma_f32_16x16x32_bf16 v[126:129], v[152:155], v[184:187], v[126:129]
	v_mfma_f32_16x16x32_bf16 v[126:129], v[156:159], v[188:191], v[126:129]
	v_mfma_f32_16x16x32_bf16 v[114:117], v[168:171], v[184:187], v[114:117]
	v_mfma_f32_16x16x32_bf16 v[114:117], v[172:175], v[188:191], v[114:117]
	v_mfma_f32_16x16x32_bf16 v[122:125], v[160:163], v[184:187], v[122:125]
	v_mfma_f32_16x16x32_bf16 v[122:125], v[164:167], v[188:191], v[122:125]
	v_mfma_f32_16x16x32_bf16 v[106:109], v[176:179], v[184:187], v[106:109]
	v_mfma_f32_16x16x32_bf16 v[106:109], v[180:183], v[188:191], v[106:109]
	v_mfma_f32_16x16x32_bf16 v[118:121], v[152:155], v[192:195], v[118:121]
	v_mfma_f32_16x16x32_bf16 v[118:121], v[156:159], v[196:199], v[118:121]
	v_mfma_f32_16x16x32_bf16 v[98:101], v[168:171], v[192:195], v[98:101]
	v_mfma_f32_16x16x32_bf16 v[98:101], v[172:175], v[196:199], v[98:101]
	v_mfma_f32_16x16x32_bf16 v[110:113], v[160:163], v[192:195], v[110:113]
	v_mfma_f32_16x16x32_bf16 v[110:113], v[164:167], v[196:199], v[110:113]
	v_mfma_f32_16x16x32_bf16 v[90:93], v[176:179], v[192:195], v[90:93]
	v_mfma_f32_16x16x32_bf16 v[90:93], v[180:183], v[196:199], v[90:93]
	s_setprio 0
	s_setprio 1
	v_mfma_f32_16x16x32_bf16 v[102:105], v[152:155], v[200:203], v[102:105]
	v_mfma_f32_16x16x32_bf16 v[102:105], v[156:159], v[204:207], v[102:105]
	v_mfma_f32_16x16x32_bf16 v[82:85], v[168:171], v[200:203], v[82:85]
	v_mfma_f32_16x16x32_bf16 v[82:85], v[172:175], v[204:207], v[82:85]
	v_mfma_f32_16x16x32_bf16 v[94:97], v[160:163], v[200:203], v[94:97]
	v_mfma_f32_16x16x32_bf16 v[94:97], v[164:167], v[204:207], v[94:97]
	v_mfma_f32_16x16x32_bf16 v[74:77], v[176:179], v[200:203], v[74:77]
	v_mfma_f32_16x16x32_bf16 v[74:77], v[180:183], v[204:207], v[74:77]
	v_mfma_f32_16x16x32_bf16 v[86:89], v[152:155], v[210:213], v[86:89]
	v_mfma_f32_16x16x32_bf16 v[86:89], v[156:159], v[214:217], v[86:89]
	v_mfma_f32_16x16x32_bf16 v[70:73], v[168:171], v[210:213], v[70:73]
	v_mfma_f32_16x16x32_bf16 v[70:73], v[172:175], v[214:217], v[70:73]
	v_mfma_f32_16x16x32_bf16 v[78:81], v[160:163], v[210:213], v[78:81]
	v_mfma_f32_16x16x32_bf16 v[78:81], v[164:167], v[214:217], v[78:81]
	v_mfma_f32_16x16x32_bf16 v[66:69], v[176:179], v[210:213], v[66:69]
	v_mfma_f32_16x16x32_bf16 v[66:69], v[180:183], v[214:217], v[66:69]
	s_setprio 0
	s_barrier
; #define PG8_STAGE(bufoff, gbase, voff) do { _Pragma("unroll") for (int _i = 0; _i < 2; ++_i) \
;         __builtin_amdgcn_global_load_lds((const unsigned*)((const char*)(gbase) + (voff)[_i]), (PG8_LAS unsigned*)(lds + (bufoff) + ldsw + _i * 8192), 16, 0, 0); } while (0)
; #define PG8_LDA(dst, b, h) do { _Pragma("unroll") for (int m = 0; m < 4; ++m) _Pragma("unroll") for (int k = 0; k < 2; ++k) dst[m][k] = *(const PG8_LAS bf16x8*)(lds + PG8_SA(b, h) + aoff + m * 2048 + k * 1024); } while (0)
; #define PG8_MMA(ai, bj, At, Bt) do { __builtin_amdgcn_s_setprio(1); _Pragma("unroll") for (int m = 0; m < 4; ++m) _Pragma("unroll") for (int n = 0; n < 2; ++n) _Pragma("unroll") for (int k = 0; k < 2; ++k) \
;         acc[ai][bj][m][n] = __builtin_amdgcn_mfma_f32_16x16x32_bf16(Bt[n][k], At[m][k], acc[ai][bj][m][n], 0, 0, 0); __builtin_amdgcn_s_setprio(0); } while (0)
; #define PG8_WAIT_V(n) asm volatile("s_waitcnt vmcnt(" #n ")" ::: "memory")
; #define PG8_WAIT_L(n) asm volatile("s_waitcnt lgkmcnt(" #n ")" ::: "memory")
; #define PG8_BAR __builtin_amdgcn_s_barrier()
; #define PG8_SCHED __builtin_amdgcn_sched_barrier(0)
; template <class Epi, class Sched, bool ALIGN_EPI = false, bool SP2 = false>
; __device__ __forceinline__ void gemm_phase(PG8_LAS unsigned char* lds, const Gemm g, const Sched& S, const Epi& E) {
;     ...
;         for (int t = 0; t < nt; t += 2) {
;     ...
;             PG8_LDA(At, 1, 1); PG8_STAGE(PG8_SB(1, 0), b3, voffB); PG8_STAGE(PG8_SB(1, 1), b3 + hstep, voffB); PG8_STAGE(PG8_SA(1, 0), a3, voffA);
;             PG8_WAIT_V(8); PG8_WAIT_L(0); PG8_BAR; PG8_MMA(1, 0, At, B0); PG8_MMA(1, 1, At, B1); PG8_BAR; PG8_SCHED;
	s_add_i32 s34, s62, s37
	v_lshl_add_u64 v[144:145], v[144:145], 0, s[6:7]
	s_mov_b32 m0, s34
	ds_read_b128 v[184:187], v151 offset:49152
	ds_read_b128 v[188:191], v151 offset:50176
	ds_read_b128 v[192:195], v151 offset:51200
	ds_read_b128 v[196:199], v151 offset:52224
	ds_read_b128 v[200:203], v151 offset:53248
	ds_read_b128 v[204:207], v151 offset:54272
	ds_read_b128 v[210:213], v151 offset:55296
	ds_read_b128 v[214:217], v151 offset:56320
	global_load_lds_dwordx4 v[144:145], off
	s_add_i32 m0, s34, 0x2000
	s_add_u32 s30, s30, 0x80080
	v_lshl_add_u64 v[144:145], v[218:219], 0, s[6:7]
	s_addc_u32 s31, s31, 0
	s_add_i32 s34, s63, s37
	global_load_lds_dwordx4 v[144:145], off
	v_lshl_add_u64 v[144:145], s[30:31], 0, v[134:135]
	s_mov_b32 m0, s34
	s_nop 0
	global_load_lds_dwordx4 v[144:145], off
	v_lshl_add_u64 v[144:145], s[30:31], 0, v[130:131]
	s_add_i32 m0, s34, 0x2000
	s_nop 0
	global_load_lds_dwordx4 v[144:145], off
	v_lshl_add_u64 v[144:145], v[220:221], 0, s[6:7]
	s_mov_b32 m0, s48
	s_nop 0
	global_load_lds_dwordx4 v[144:145], off
	v_lshl_add_u64 v[144:145], v[222:223], 0, s[6:7]
	s_mov_b32 m0, s49
	s_nop 0
	global_load_lds_dwordx4 v[144:145], off
	s_waitcnt vmcnt(8)
	s_waitcnt lgkmcnt(0)
	s_barrier
	s_setprio 1
	s_waitcnt lgkmcnt(0)
	v_mfma_f32_16x16x32_bf16 v[62:65], v[152:155], v[184:187], v[62:65]
	v_mfma_f32_16x16x32_bf16 v[62:65], v[156:159], v[188:191], v[62:65]
	v_mfma_f32_16x16x32_bf16 v[50:53], v[168:171], v[184:187], v[50:53]
	v_mfma_f32_16x16x32_bf16 v[50:53], v[172:175], v[188:191], v[50:53]
	v_mfma_f32_16x16x32_bf16 v[58:61], v[160:163], v[184:187], v[58:61]
	v_mfma_f32_16x16x32_bf16 v[58:61], v[164:167], v[188:191], v[58:61]
	v_mfma_f32_16x16x32_bf16 v[42:45], v[176:179], v[184:187], v[42:45]
	v_mfma_f32_16x16x32_bf16 v[42:45], v[180:183], v[188:191], v[42:45]
	v_mfma_f32_16x16x32_bf16 v[54:57], v[152:155], v[192:195], v[54:57]
	v_mfma_f32_16x16x32_bf16 v[54:57], v[156:159], v[196:199], v[54:57]
	v_mfma_f32_16x16x32_bf16 v[34:37], v[168:171], v[192:195], v[34:37]
	v_mfma_f32_16x16x32_bf16 v[34:37], v[172:175], v[196:199], v[34:37]
	v_mfma_f32_16x16x32_bf16 v[46:49], v[160:163], v[192:195], v[46:49]
	v_mfma_f32_16x16x32_bf16 v[46:49], v[164:167], v[196:199], v[46:49]
	v_mfma_f32_16x16x32_bf16 v[26:29], v[176:179], v[192:195], v[26:29]
	v_mfma_f32_16x16x32_bf16 v[26:29], v[180:183], v[196:199], v[26:29]
	s_setprio 0
	s_setprio 1
	v_mfma_f32_16x16x32_bf16 v[38:41], v[152:155], v[200:203], v[38:41]
	v_mfma_f32_16x16x32_bf16 v[38:41], v[156:159], v[204:207], v[38:41]
	v_mfma_f32_16x16x32_bf16 v[18:21], v[168:171], v[200:203], v[18:21]
	v_mfma_f32_16x16x32_bf16 v[18:21], v[172:175], v[204:207], v[18:21]
	v_mfma_f32_16x16x32_bf16 v[30:33], v[160:163], v[200:203], v[30:33]
	v_mfma_f32_16x16x32_bf16 v[30:33], v[164:167], v[204:207], v[30:33]
	v_mfma_f32_16x16x32_bf16 v[10:13], v[176:179], v[200:203], v[10:13]
	v_mfma_f32_16x16x32_bf16 v[10:13], v[180:183], v[204:207], v[10:13]
	v_mfma_f32_16x16x32_bf16 v[22:25], v[152:155], v[210:213], v[22:25]
	v_mfma_f32_16x16x32_bf16 v[22:25], v[156:159], v[214:217], v[22:25]
	v_mfma_f32_16x16x32_bf16 v[6:9], v[168:171], v[210:213], v[6:9]
	v_mfma_f32_16x16x32_bf16 v[6:9], v[172:175], v[214:217], v[6:9]
	v_mfma_f32_16x16x32_bf16 v[14:17], v[160:163], v[210:213], v[14:17]
	v_mfma_f32_16x16x32_bf16 v[14:17], v[164:167], v[214:217], v[14:17]
	v_mfma_f32_16x16x32_bf16 v[2:5], v[176:179], v[210:213], v[2:5]
	v_mfma_f32_16x16x32_bf16 v[2:5], v[180:183], v[214:217], v[2:5]
	s_setprio 0
	s_barrier
	s_add_i32 s61, s61, 2
	s_add_u32 s28, s28, 0x100
	s_addc_u32 s29, s29, 0
	s_add_u32 s59, s59, 0x100
	s_addc_u32 s60, s60, 0
	s_cmp_gt_u32 s61, 29
	s_cbranch_scc0 .LBB11_228
	s_and_b64 vcc, exec, s[8:9]
	s_cbranch_vccz .LBB11_231
	s_barrier

; #define PG8_STAGE(bufoff, gbase, voff) do { _Pragma("unroll") for (int _i = 0; _i < 2; ++_i) \
;         __builtin_amdgcn_global_load_lds((const unsigned*)((const char*)(gbase) + (voff)[_i]), (PG8_LAS unsigned*)(lds + (bufoff) + ldsw + _i * 8192), 16, 0, 0); } while (0)
; #define PG8_LDA(dst, b, h) do { _Pragma("unroll") for (int m = 0; m < 4; ++m) _Pragma("unroll") for (int k = 0; k < 2; ++k) dst[m][k] = *(const PG8_LAS bf16x8*)(lds + PG8_SA(b, h) + aoff + m * 2048 + k * 1024); } while (0)
; #define PG8_LDB(dst, b, h) do { _Pragma("unroll") for (int n = 0; n < 2; ++n) _Pragma("unroll") for (int k = 0; k < 2; ++k) dst[n][k] = *(const PG8_LAS bf16x8*)(lds + PG8_SB(b, h) + boff + n * 2048 + k * 1024); } while (0)
; #define PG8_MMA(ai, bj, At, Bt) do { __builtin_amdgcn_s_setprio(1); _Pragma("unroll") for (int m = 0; m < 4; ++m) _Pragma("unroll") for (int n = 0; n < 2; ++n) _Pragma("unroll") for (int k = 0; k < 2; ++k) \
;         acc[ai][bj][m][n] = __builtin_amdgcn_mfma_f32_16x16x32_bf16(Bt[n][k], At[m][k], acc[ai][bj][m][n], 0, 0, 0); __builtin_amdgcn_s_setprio(0); } while (0)
; #define PG8_WAIT_V(n) asm volatile("s_waitcnt vmcnt(" #n ")" ::: "memory")
; #define PG8_WAIT_L(n) asm volatile("s_waitcnt lgkmcnt(" #n ")" ::: "memory")
; template <class Epi, class Sched, bool ALIGN_EPI = false, bool SP2 = false>
; __device__ __forceinline__ void gemm_phase(PG8_LAS unsigned char* lds, const Gemm g, const Sched& S, const Epi& E) {
;     ...
;             const bool last = (t == nt - 2);
;             const char* a1 = cA + (size_t)(t + 1) * kstep;
;             const char* a2 = last ? nA : cA + (size_t)(t + 2) * kstep; const char* b2 = last ? nB : cB + (size_t)(t + 2) * kstep;
;             const char* a3 = a2 + kstep; const char* b3 = b2 + kstep;
;             if (last && has_next) S.a_ready(nxt);
;             if constexpr (SP2) {
;             PG8_LDB(B0, 0, 0); PG8_LDB(B1, 0, 1); PG8_SCHED; PG8_LDA(At, 0, 0); PG8_STAGE(PG8_SA(1, 1), a1 + hstep, voffA);
;             PG8_WAIT_V(8); PG8_WAIT_L(0); PG8_BAR; PG8_MMA(0, 0, At, B0); PG8_MMA(0, 1, At, B1); PG8_BAR; PG8_SCHED;
;             PG8_LDA(At, 0, 1); PG8_STAGE(PG8_SB(0, 0), b2, voffB); PG8_STAGE(PG8_SB(0, 1), b2 + hstep, voffB); PG8_STAGE(PG8_SA(0, 0), a2, voffA);
;             PG8_WAIT_V(8); PG8_WAIT_L(0); PG8_BAR; PG8_MMA(1, 0, At, B0); PG8_MMA(1, 1, At, B1); PG8_BAR; PG8_SCHED;
.LBB11_456:
	s_add_u32 s18, s16, 0xfff80080
	s_addc_u32 s19, s17, -1
	s_add_i32 s49, 0, 0x10000
	s_cmp_eq_u32 s48, 28
	s_cselect_b32 s21, s11, s19
	s_cselect_b32 s20, s44, s18
	v_add_u32_e32 v144, s49, v147
	s_cselect_b32 s19, s9, s47
	s_cselect_b32 s18, s45, s46
	s_add_i32 s52, 0, 0x14000
	ds_read_b128 v[150:153], v144
	ds_read_b128 v[154:157], v144 offset:1024
	ds_read_b128 v[158:161], v144 offset:2048
	ds_read_b128 v[162:165], v144 offset:3072
	v_add_u32_e32 v144, s52, v147
	ds_read_b128 v[166:169], v144
	ds_read_b128 v[170:173], v144 offset:1024
	ds_read_b128 v[174:177], v144 offset:2048
	ds_read_b128 v[178:181], v144 offset:3072
	v_lshl_add_u64 v[144:145], s[16:17], 0, v[140:141]
	s_add_i32 m0, s29, 0xc000
	ds_read_b128 v[198:201], v149
	ds_read_b128 v[202:205], v149 offset:1024
	ds_read_b128 v[220:223], v149 offset:2048
	ds_read_b128 v[224:227], v149 offset:3072
	ds_read_b128 v[228:231], v149 offset:4096
	ds_read_b128 v[232:235], v149 offset:5120
	ds_read_b128 v[236:239], v149 offset:6144
	ds_read_b128 v[240:243], v149 offset:7168
	global_load_lds_dwordx4 v[144:145], off
	v_lshl_add_u64 v[144:145], s[16:17], 0, v[142:143]
	s_add_i32 m0, s29, 0xe000
	s_nop 0
	global_load_lds_dwordx4 v[144:145], off
	s_waitcnt vmcnt(8)
	s_waitcnt lgkmcnt(0)
	s_barrier
	s_setprio 1
	s_waitcnt lgkmcnt(0)
	v_mfma_f32_16x16x32_bf16 v[124:127], v[150:153], v[198:201], v[124:127]
	v_mfma_f32_16x16x32_bf16 v[124:127], v[154:157], v[202:205], v[124:127]
	v_mfma_f32_16x16x32_bf16 v[128:131], v[166:169], v[198:201], v[128:131]
	v_mfma_f32_16x16x32_bf16 v[128:131], v[170:173], v[202:205], v[128:131]
	v_mfma_f32_16x16x32_bf16 v[116:119], v[158:161], v[198:201], v[116:119]
	v_mfma_f32_16x16x32_bf16 v[116:119], v[162:165], v[202:205], v[116:119]
	v_mfma_f32_16x16x32_bf16 v[120:123], v[174:177], v[198:201], v[120:123]
	v_mfma_f32_16x16x32_bf16 v[120:123], v[178:181], v[202:205], v[120:123]
	v_mfma_f32_16x16x32_bf16 v[108:111], v[150:153], v[220:223], v[108:111]
	v_mfma_f32_16x16x32_bf16 v[108:111], v[154:157], v[224:227], v[108:111]
	v_mfma_f32_16x16x32_bf16 v[112:115], v[166:169], v[220:223], v[112:115]
	v_mfma_f32_16x16x32_bf16 v[112:115], v[170:173], v[224:227], v[112:115]
	v_mfma_f32_16x16x32_bf16 v[100:103], v[158:161], v[220:223], v[100:103]
	v_mfma_f32_16x16x32_bf16 v[100:103], v[162:165], v[224:227], v[100:103]
	v_mfma_f32_16x16x32_bf16 v[104:107], v[174:177], v[220:223], v[104:107]
	v_mfma_f32_16x16x32_bf16 v[104:107], v[178:181], v[224:227], v[104:107]
	s_setprio 0
	s_setprio 1
	v_mfma_f32_16x16x32_bf16 v[92:95], v[150:153], v[228:231], v[92:95]
	v_mfma_f32_16x16x32_bf16 v[92:95], v[154:157], v[232:235], v[92:95]
	v_mfma_f32_16x16x32_bf16 v[96:99], v[166:169], v[228:231], v[96:99]
	v_mfma_f32_16x16x32_bf16 v[96:99], v[170:173], v[232:235], v[96:99]
	v_mfma_f32_16x16x32_bf16 v[84:87], v[158:161], v[228:231], v[84:87]
	v_mfma_f32_16x16x32_bf16 v[84:87], v[162:165], v[232:235], v[84:87]
	v_mfma_f32_16x16x32_bf16 v[88:91], v[174:177], v[228:231], v[88:91]
	v_mfma_f32_16x16x32_bf16 v[88:91], v[178:181], v[232:235], v[88:91]
	v_mfma_f32_16x16x32_bf16 v[76:79], v[150:153], v[236:239], v[76:79]
	v_mfma_f32_16x16x32_bf16 v[76:79], v[154:157], v[240:243], v[76:79]
	v_mfma_f32_16x16x32_bf16 v[80:83], v[166:169], v[236:239], v[80:83]
	v_mfma_f32_16x16x32_bf16 v[80:83], v[170:173], v[240:243], v[80:83]
	v_mfma_f32_16x16x32_bf16 v[68:71], v[158:161], v[236:239], v[68:71]
	v_mfma_f32_16x16x32_bf16 v[68:71], v[162:165], v[240:243], v[68:71]
	v_mfma_f32_16x16x32_bf16 v[72:75], v[174:177], v[236:239], v[72:75]
	v_mfma_f32_16x16x32_bf16 v[72:75], v[178:181], v[240:243], v[72:75]
	s_setprio 0
	s_barrier
	s_add_i32 s49, s49, s27
	v_lshl_add_u64 v[144:145], s[18:19], 0, v[2:3]
	s_mov_b32 m0, s49
	ds_read_b128 v[198:201], v149 offset:16384
	ds_read_b128 v[202:205], v149 offset:17408
	ds_read_b128 v[220:223], v149 offset:18432
	ds_read_b128 v[224:227], v149 offset:19456
	ds_read_b128 v[228:231], v149 offset:20480
	ds_read_b128 v[232:235], v149 offset:21504
	ds_read_b128 v[236:239], v149 offset:22528
	ds_read_b128 v[240:243], v149 offset:23552
	global_load_lds_dwordx4 v[144:145], off
	s_add_i32 m0, s49, 0x2000
	s_add_u32 s50, s18, 0x80000
	v_lshl_add_u64 v[206:207], s[18:19], 0, v[132:133]
	s_addc_u32 s51, s19, 0
	s_add_i32 s49, s52, s27
	global_load_lds_dwordx4 v[206:207], off
	v_lshl_add_u64 v[244:245], s[50:51], 0, v[2:3]
	s_mov_b32 m0, s49
	v_lshl_add_u64 v[246:247], s[20:21], 0, v[134:135]
	global_load_lds_dwordx4 v[244:245], off
	v_lshl_add_u64 v[244:245], s[50:51], 0, v[132:133]
	s_add_i32 m0, s49, 0x2000
	s_nop 0
	global_load_lds_dwordx4 v[244:245], off
	v_lshl_add_u64 v[244:245], s[20:21], 0, v[136:137]
	s_mov_b32 m0, s29
	s_nop 0
	global_load_lds_dwordx4 v[244:245], off
	s_mov_b32 m0, s30
	s_nop 0
	global_load_lds_dwordx4 v[246:247], off
	s_waitcnt vmcnt(8)
	s_waitcnt lgkmcnt(0)
	s_barrier
; #define PG8_STAGE(bufoff, gbase, voff) do { _Pragma("unroll") for (int _i = 0; _i < 2; ++_i) \
;         __builtin_amdgcn_global_load_lds((const unsigned*)((const char*)(gbase) + (voff)[_i]), (PG8_LAS unsigned*)(lds + (bufoff) + ldsw + _i * 8192), 16, 0, 0); } while (0)
; #define PG8_LDA(dst, b, h) do { _Pragma("unroll") for (int m = 0; m < 4; ++m) _Pragma("unroll") for (int k = 0; k < 2; ++k) dst[m][k] = *(const PG8_LAS bf16x8*)(lds + PG8_SA(b, h) + aoff + m * 2048 + k * 1024); } while (0)
; #define PG8_LDB(dst, b, h) do { _Pragma("unroll") for (int n = 0; n < 2; ++n) _Pragma("unroll") for (int k = 0; k < 2; ++k) dst[n][k] = *(const PG8_LAS bf16x8*)(lds + PG8_SB(b, h) + boff + n * 2048 + k * 1024); } while (0)
; #define PG8_MMA(ai, bj, At, Bt) do { __builtin_amdgcn_s_setprio(1); _Pragma("unroll") for (int m = 0; m < 4; ++m) _Pragma("unroll") for (int n = 0; n < 2; ++n) _Pragma("unroll") for (int k = 0; k < 2; ++k) \
;         acc[ai][bj][m][n] = __builtin_amdgcn_mfma_f32_16x16x32_bf16(Bt[n][k], At[m][k], acc[ai][bj][m][n], 0, 0, 0); __builtin_amdgcn_s_setprio(0); } while (0)
; #define PG8_WAIT_V(n) asm volatile("s_waitcnt vmcnt(" #n ")" ::: "memory")
; #define PG8_WAIT_L(n) asm volatile("s_waitcnt lgkmcnt(" #n ")" ::: "memory")
; #define PG8_BAR __builtin_amdgcn_s_barrier()
; #define PG8_SCHED __builtin_amdgcn_sched_barrier(0)
; template <class Epi, class Sched, bool ALIGN_EPI = false, bool SP2 = false>
; __device__ __forceinline__ void gemm_phase(PG8_LAS unsigned char* lds, const Gemm g, const Sched& S, const Epi& E) {
;     ...
;             PG8_WAIT_V(8); PG8_WAIT_L(0); PG8_BAR; PG8_MMA(1, 0, At, B0); PG8_MMA(1, 1, At, B1); PG8_BAR; PG8_SCHED;
;             PG8_LDB(B0, 1, 0); PG8_LDB(B1, 1, 1); PG8_SCHED; PG8_LDA(At, 1, 0); PG8_STAGE(PG8_SA(0, 1), a2 + hstep, voffA);
;             PG8_WAIT_V(8); PG8_WAIT_L(0); PG8_BAR; PG8_MMA(0, 0, At, B0); PG8_MMA(0, 1, At, B1); PG8_BAR; PG8_SCHED;
	s_setprio 1
	s_waitcnt lgkmcnt(0)
	v_mfma_f32_16x16x32_bf16 v[60:63], v[150:153], v[198:201], v[60:63]
	v_mfma_f32_16x16x32_bf16 v[60:63], v[154:157], v[202:205], v[60:63]
	v_mfma_f32_16x16x32_bf16 v[64:67], v[166:169], v[198:201], v[64:67]
	v_mfma_f32_16x16x32_bf16 v[64:67], v[170:173], v[202:205], v[64:67]
	v_mfma_f32_16x16x32_bf16 v[52:55], v[158:161], v[198:201], v[52:55]
	v_mfma_f32_16x16x32_bf16 v[52:55], v[162:165], v[202:205], v[52:55]
	v_mfma_f32_16x16x32_bf16 v[56:59], v[174:177], v[198:201], v[56:59]
	v_mfma_f32_16x16x32_bf16 v[56:59], v[178:181], v[202:205], v[56:59]
	v_mfma_f32_16x16x32_bf16 v[44:47], v[150:153], v[220:223], v[44:47]
	v_mfma_f32_16x16x32_bf16 v[44:47], v[154:157], v[224:227], v[44:47]
	v_mfma_f32_16x16x32_bf16 v[48:51], v[166:169], v[220:223], v[48:51]
	v_mfma_f32_16x16x32_bf16 v[48:51], v[170:173], v[224:227], v[48:51]
	v_mfma_f32_16x16x32_bf16 v[36:39], v[158:161], v[220:223], v[36:39]
	v_mfma_f32_16x16x32_bf16 v[36:39], v[162:165], v[224:227], v[36:39]
	v_mfma_f32_16x16x32_bf16 v[40:43], v[174:177], v[220:223], v[40:43]
	v_mfma_f32_16x16x32_bf16 v[40:43], v[178:181], v[224:227], v[40:43]
	s_setprio 0
	s_setprio 1
	v_mfma_f32_16x16x32_bf16 v[28:31], v[150:153], v[228:231], v[28:31]
	v_mfma_f32_16x16x32_bf16 v[28:31], v[154:157], v[232:235], v[28:31]
	v_mfma_f32_16x16x32_bf16 v[32:35], v[166:169], v[228:231], v[32:35]
	v_mfma_f32_16x16x32_bf16 v[32:35], v[170:173], v[232:235], v[32:35]
	v_mfma_f32_16x16x32_bf16 v[20:23], v[158:161], v[228:231], v[20:23]
	v_mfma_f32_16x16x32_bf16 v[20:23], v[162:165], v[232:235], v[20:23]
	v_mfma_f32_16x16x32_bf16 v[24:27], v[174:177], v[228:231], v[24:27]
	v_mfma_f32_16x16x32_bf16 v[24:27], v[178:181], v[232:235], v[24:27]
	v_mfma_f32_16x16x32_bf16 v[12:15], v[150:153], v[236:239], v[12:15]
	v_mfma_f32_16x16x32_bf16 v[12:15], v[154:157], v[240:243], v[12:15]
	v_mfma_f32_16x16x32_bf16 v[16:19], v[166:169], v[236:239], v[16:19]
	v_mfma_f32_16x16x32_bf16 v[16:19], v[170:173], v[240:243], v[16:19]
	v_mfma_f32_16x16x32_bf16 v[4:7], v[158:161], v[236:239], v[4:7]
	v_mfma_f32_16x16x32_bf16 v[4:7], v[162:165], v[240:243], v[4:7]
	v_mfma_f32_16x16x32_bf16 v[8:11], v[174:177], v[236:239], v[8:11]
	v_mfma_f32_16x16x32_bf16 v[8:11], v[178:181], v[240:243], v[8:11]
	s_setprio 0
	s_barrier
	s_add_i32 s49, 0, 0x18000
	s_add_i32 s50, 0, 0x1c000
	v_add_u32_e32 v162, s49, v147
	v_add_u32_e32 v178, s50, v147
	ds_read_b128 v[150:153], v162
	ds_read_b128 v[154:157], v162 offset:1024
	ds_read_b128 v[158:161], v162 offset:2048
	ds_read_b128 v[162:165], v162 offset:3072
	ds_read_b128 v[166:169], v178
	ds_read_b128 v[170:173], v178 offset:1024
	ds_read_b128 v[174:177], v178 offset:2048
	ds_read_b128 v[178:181], v178 offset:3072
	s_add_u32 s20, s20, 0x80000
	s_addc_u32 s21, s21, 0
	s_mov_b32 m0, s33
	v_lshl_add_u64 v[196:197], s[20:21], 0, v[136:137]
	ds_read_b128 v[198:201], v149 offset:32768
	ds_read_b128 v[202:205], v149 offset:33792
	ds_read_b128 v[220:223], v149 offset:34816
	ds_read_b128 v[224:227], v149 offset:35840
	ds_read_b128 v[228:231], v149 offset:36864
	ds_read_b128 v[232:235], v149 offset:37888
	ds_read_b128 v[236:239], v149 offset:38912
	ds_read_b128 v[240:243], v149 offset:39936
	global_load_lds_dwordx4 v[196:197], off
	v_lshl_add_u64 v[196:197], s[20:21], 0, v[134:135]
	s_mov_b32 m0, s38
	s_nop 0
	global_load_lds_dwordx4 v[196:197], off
	s_waitcnt vmcnt(8)
	s_waitcnt lgkmcnt(0)
	s_barrier
	s_setprio 1
	s_waitcnt lgkmcnt(0)
	v_mfma_f32_16x16x32_bf16 v[124:127], v[150:153], v[198:201], v[124:127]
	v_mfma_f32_16x16x32_bf16 v[124:127], v[154:157], v[202:205], v[124:127]
	v_mfma_f32_16x16x32_bf16 v[128:131], v[166:169], v[198:201], v[128:131]
	v_mfma_f32_16x16x32_bf16 v[128:131], v[170:173], v[202:205], v[128:131]
	v_mfma_f32_16x16x32_bf16 v[116:119], v[158:161], v[198:201], v[116:119]
	v_mfma_f32_16x16x32_bf16 v[116:119], v[162:165], v[202:205], v[116:119]
	v_mfma_f32_16x16x32_bf16 v[120:123], v[174:177], v[198:201], v[120:123]
	v_mfma_f32_16x16x32_bf16 v[120:123], v[178:181], v[202:205], v[120:123]
	v_mfma_f32_16x16x32_bf16 v[108:111], v[150:153], v[220:223], v[108:111]
	v_mfma_f32_16x16x32_bf16 v[108:111], v[154:157], v[224:227], v[108:111]
	v_mfma_f32_16x16x32_bf16 v[112:115], v[166:169], v[220:223], v[112:115]
	v_mfma_f32_16x16x32_bf16 v[112:115], v[170:173], v[224:227], v[112:115]
	v_mfma_f32_16x16x32_bf16 v[100:103], v[158:161], v[220:223], v[100:103]
	v_mfma_f32_16x16x32_bf16 v[100:103], v[162:165], v[224:227], v[100:103]
	v_mfma_f32_16x16x32_bf16 v[104:107], v[174:177], v[220:223], v[104:107]
	v_mfma_f32_16x16x32_bf16 v[104:107], v[178:181], v[224:227], v[104:107]
	s_setprio 0
	s_setprio 1
	v_mfma_f32_16x16x32_bf16 v[92:95], v[150:153], v[228:231], v[92:95]
	v_mfma_f32_16x16x32_bf16 v[92:95], v[154:157], v[232:235], v[92:95]
	v_mfma_f32_16x16x32_bf16 v[96:99], v[166:169], v[228:231], v[96:99]
	v_mfma_f32_16x16x32_bf16 v[96:99], v[170:173], v[232:235], v[96:99]
	v_mfma_f32_16x16x32_bf16 v[84:87], v[158:161], v[228:231], v[84:87]
	v_mfma_f32_16x16x32_bf16 v[84:87], v[162:165], v[232:235], v[84:87]
	v_mfma_f32_16x16x32_bf16 v[88:91], v[174:177], v[228:231], v[88:91]
	v_mfma_f32_16x16x32_bf16 v[88:91], v[178:181], v[232:235], v[88:91]
	v_mfma_f32_16x16x32_bf16 v[76:79], v[150:153], v[236:239], v[76:79]
	v_mfma_f32_16x16x32_bf16 v[76:79], v[154:157], v[240:243], v[76:79]
	v_mfma_f32_16x16x32_bf16 v[80:83], v[166:169], v[236:239], v[80:83]
	v_mfma_f32_16x16x32_bf16 v[80:83], v[170:173], v[240:243], v[80:83]
	v_mfma_f32_16x16x32_bf16 v[68:71], v[158:161], v[236:239], v[68:71]
	v_mfma_f32_16x16x32_bf16 v[68:71], v[162:165], v[240:243], v[68:71]
	v_mfma_f32_16x16x32_bf16 v[72:75], v[174:177], v[236:239], v[72:75]
	v_mfma_f32_16x16x32_bf16 v[72:75], v[178:181], v[240:243], v[72:75]
	s_setprio 0
	s_barrier
; #define PG8_STAGE(bufoff, gbase, voff) do { _Pragma("unroll") for (int _i = 0; _i < 2; ++_i) \
;         __builtin_amdgcn_global_load_lds((const unsigned*)((const char*)(gbase) + (voff)[_i]), (PG8_LAS unsigned*)(lds + (bufoff) + ldsw + _i * 8192), 16, 0, 0); } while (0)
; #define PG8_LDA(dst, b, h) do { _Pragma("unroll") for (int m = 0; m < 4; ++m) _Pragma("unroll") for (int k = 0; k < 2; ++k) dst[m][k] = *(const PG8_LAS bf16x8*)(lds + PG8_SA(b, h) + aoff + m * 2048 + k * 1024); } while (0)
; #define PG8_MMA(ai, bj, At, Bt) do { __builtin_amdgcn_s_setprio(1); _Pragma("unroll") for (int m = 0; m < 4; ++m) _Pragma("unroll") for (int n = 0; n < 2; ++n) _Pragma("unroll") for (int k = 0; k < 2; ++k) \
;         acc[ai][bj][m][n] = __builtin_amdgcn_mfma_f32_16x16x32_bf16(Bt[n][k], At[m][k], acc[ai][bj][m][n], 0, 0, 0); __builtin_amdgcn_s_setprio(0); } while (0)
; #define PG8_WAIT_V(n) asm volatile("s_waitcnt vmcnt(" #n ")" ::: "memory")
; #define PG8_WAIT_L(n) asm volatile("s_waitcnt lgkmcnt(" #n ")" ::: "memory")
; #define PG8_BAR __builtin_amdgcn_s_barrier()
; #define PG8_SCHED __builtin_amdgcn_sched_barrier(0)
; template <class Epi, class Sched, bool ALIGN_EPI = false, bool SP2 = false>
; __device__ __forceinline__ void gemm_phase(PG8_LAS unsigned char* lds, const Gemm g, const Sched& S, const Epi& E) {
;     ...
;         for (int t = 0; t < nt; t += 2) {
;     ...
;             PG8_LDA(At, 1, 1); PG8_STAGE(PG8_SB(1, 0), b3, voffB); PG8_STAGE(PG8_SB(1, 1), b3 + hstep, voffB); PG8_STAGE(PG8_SA(1, 0), a3, voffA);
;             PG8_WAIT_V(8); PG8_WAIT_L(0); PG8_BAR; PG8_MMA(1, 0, At, B0); PG8_MMA(1, 1, At, B1); PG8_BAR; PG8_SCHED;
	s_add_i32 s20, s49, s27
	v_lshl_add_u64 v[144:145], v[144:145], 0, s[34:35]
	s_mov_b32 m0, s20
	ds_read_b128 v[198:201], v149 offset:49152
	ds_read_b128 v[202:205], v149 offset:50176
	ds_read_b128 v[220:223], v149 offset:51200
	ds_read_b128 v[224:227], v149 offset:52224
	ds_read_b128 v[228:231], v149 offset:53248
	ds_read_b128 v[232:235], v149 offset:54272
	ds_read_b128 v[236:239], v149 offset:55296
	ds_read_b128 v[240:243], v149 offset:56320
	global_load_lds_dwordx4 v[144:145], off
	s_add_i32 m0, s20, 0x2000
	s_add_u32 s18, s18, 0x80080
	v_lshl_add_u64 v[144:145], v[206:207], 0, s[34:35]
	s_addc_u32 s19, s19, 0
	s_add_i32 s20, s50, s27
	global_load_lds_dwordx4 v[144:145], off
	v_lshl_add_u64 v[144:145], s[18:19], 0, v[2:3]
	s_mov_b32 m0, s20
	s_nop 0
	global_load_lds_dwordx4 v[144:145], off
	v_lshl_add_u64 v[144:145], s[18:19], 0, v[132:133]
	s_add_i32 m0, s20, 0x2000
	s_nop 0
	global_load_lds_dwordx4 v[144:145], off
	v_lshl_add_u64 v[144:145], v[244:245], 0, s[34:35]
	s_mov_b32 m0, s39
	s_nop 0
	global_load_lds_dwordx4 v[144:145], off
	v_lshl_add_u64 v[144:145], v[246:247], 0, s[34:35]
	s_mov_b32 m0, s40
	s_nop 0
	global_load_lds_dwordx4 v[144:145], off
	s_waitcnt vmcnt(8)
	s_waitcnt lgkmcnt(0)
	s_barrier
	s_setprio 1
	s_waitcnt lgkmcnt(0)
	v_mfma_f32_16x16x32_bf16 v[60:63], v[150:153], v[198:201], v[60:63]
	v_mfma_f32_16x16x32_bf16 v[60:63], v[154:157], v[202:205], v[60:63]
	v_mfma_f32_16x16x32_bf16 v[64:67], v[166:169], v[198:201], v[64:67]
	v_mfma_f32_16x16x32_bf16 v[64:67], v[170:173], v[202:205], v[64:67]
	v_mfma_f32_16x16x32_bf16 v[52:55], v[158:161], v[198:201], v[52:55]
	v_mfma_f32_16x16x32_bf16 v[52:55], v[162:165], v[202:205], v[52:55]
	v_mfma_f32_16x16x32_bf16 v[56:59], v[174:177], v[198:201], v[56:59]
	v_mfma_f32_16x16x32_bf16 v[56:59], v[178:181], v[202:205], v[56:59]
	v_mfma_f32_16x16x32_bf16 v[44:47], v[150:153], v[220:223], v[44:47]
	v_mfma_f32_16x16x32_bf16 v[44:47], v[154:157], v[224:227], v[44:47]
	v_mfma_f32_16x16x32_bf16 v[48:51], v[166:169], v[220:223], v[48:51]
	v_mfma_f32_16x16x32_bf16 v[48:51], v[170:173], v[224:227], v[48:51]
	v_mfma_f32_16x16x32_bf16 v[36:39], v[158:161], v[220:223], v[36:39]
	v_mfma_f32_16x16x32_bf16 v[36:39], v[162:165], v[224:227], v[36:39]
	v_mfma_f32_16x16x32_bf16 v[40:43], v[174:177], v[220:223], v[40:43]
	v_mfma_f32_16x16x32_bf16 v[40:43], v[178:181], v[224:227], v[40:43]
	s_setprio 0
	s_setprio 1
	v_mfma_f32_16x16x32_bf16 v[28:31], v[150:153], v[228:231], v[28:31]
	v_mfma_f32_16x16x32_bf16 v[28:31], v[154:157], v[232:235], v[28:31]
	v_mfma_f32_16x16x32_bf16 v[32:35], v[166:169], v[228:231], v[32:35]
	v_mfma_f32_16x16x32_bf16 v[32:35], v[170:173], v[232:235], v[32:35]
	v_mfma_f32_16x16x32_bf16 v[20:23], v[158:161], v[228:231], v[20:23]
	v_mfma_f32_16x16x32_bf16 v[20:23], v[162:165], v[232:235], v[20:23]
	v_mfma_f32_16x16x32_bf16 v[24:27], v[174:177], v[228:231], v[24:27]
	v_mfma_f32_16x16x32_bf16 v[24:27], v[178:181], v[232:235], v[24:27]
	v_mfma_f32_16x16x32_bf16 v[12:15], v[150:153], v[236:239], v[12:15]
	v_mfma_f32_16x16x32_bf16 v[12:15], v[154:157], v[240:243], v[12:15]
	v_mfma_f32_16x16x32_bf16 v[16:19], v[166:169], v[236:239], v[16:19]
	v_mfma_f32_16x16x32_bf16 v[16:19], v[170:173], v[240:243], v[16:19]
	v_mfma_f32_16x16x32_bf16 v[4:7], v[158:161], v[236:239], v[4:7]
	v_mfma_f32_16x16x32_bf16 v[4:7], v[162:165], v[240:243], v[4:7]
	v_mfma_f32_16x16x32_bf16 v[8:11], v[174:177], v[236:239], v[8:11]
	v_mfma_f32_16x16x32_bf16 v[8:11], v[178:181], v[240:243], v[8:11]
	s_setprio 0
	s_barrier
	s_add_i32 s48, s48, 2
	s_add_u32 s16, s16, 0x100
	s_addc_u32 s17, s17, 0
	s_add_u32 s46, s46, 0x100
	s_addc_u32 s47, s47, 0
	s_cmp_gt_u32 s48, 29
	s_cbranch_scc0 .LBB11_456
	s_and_b64 vcc, exec, s[6:7]
	s_cbranch_vccz .LBB11_459
	s_barrier

; #define PG8_STAGE(bufoff, gbase, voff) do { _Pragma("unroll") for (int _i = 0; _i < 2; ++_i) \
;         __builtin_amdgcn_global_load_lds((const unsigned*)((const char*)(gbase) + (voff)[_i]), (PG8_LAS unsigned*)(lds + (bufoff) + ldsw + _i * 8192), 16, 0, 0); } while (0)
; #define PG8_LDA(dst, b, h) do { _Pragma("unroll") for (int m = 0; m < 4; ++m) _Pragma("unroll") for (int k = 0; k < 2; ++k) dst[m][k] = *(const PG8_LAS bf16x8*)(lds + PG8_SA(b, h) + aoff + m * 2048 + k * 1024); } while (0)
; #define PG8_LDB(dst, b, h) do { _Pragma("unroll") for (int n = 0; n < 2; ++n) _Pragma("unroll") for (int k = 0; k < 2; ++k) dst[n][k] = *(const PG8_LAS bf16x8*)(lds + PG8_SB(b, h) + boff + n * 2048 + k * 1024); } while (0)
; #define PG8_MMA(ai, bj, At, Bt) do { __builtin_amdgcn_s_setprio(1); _Pragma("unroll") for (int m = 0; m < 4; ++m) _Pragma("unroll") for (int n = 0; n < 2; ++n) _Pragma("unroll") for (int k = 0; k < 2; ++k) \
;         acc[ai][bj][m][n] = __builtin_amdgcn_mfma_f32_16x16x32_bf16(Bt[n][k], At[m][k], acc[ai][bj][m][n], 0, 0, 0); __builtin_amdgcn_s_setprio(0); } while (0)
; #define PG8_WAIT_V(n) asm volatile("s_waitcnt vmcnt(" #n ")" ::: "memory")
; #define PG8_WAIT_L(n) asm volatile("s_waitcnt lgkmcnt(" #n ")" ::: "memory")
; template <class Epi, class Sched, bool ALIGN_EPI = false, bool SP2 = false>
; __device__ __forceinline__ void gemm_phase(PG8_LAS unsigned char* lds, const Gemm g, const Sched& S, const Epi& E) {
;     ...
;             const bool last = (t == nt - 2);
;             const char* a1 = cA + (size_t)(t + 1) * kstep;
;             const char* a2 = last ? nA : cA + (size_t)(t + 2) * kstep; const char* b2 = last ? nB : cB + (size_t)(t + 2) * kstep;
;             const char* a3 = a2 + kstep; const char* b3 = b2 + kstep;
;             if (last && has_next) S.a_ready(nxt);
;             if constexpr (SP2) {
;             PG8_LDB(B0, 0, 0); PG8_LDB(B1, 0, 1); PG8_SCHED; PG8_LDA(At, 0, 0); PG8_STAGE(PG8_SA(1, 1), a1 + hstep, voffA);
;             PG8_WAIT_V(8); PG8_WAIT_L(0); PG8_BAR; PG8_MMA(0, 0, At, B0); PG8_MMA(0, 1, At, B1); PG8_BAR; PG8_SCHED;
;             PG8_LDA(At, 0, 1); PG8_STAGE(PG8_SB(0, 0), b2, voffB); PG8_STAGE(PG8_SB(0, 1), b2 + hstep, voffB); PG8_STAGE(PG8_SA(0, 0), a2, voffA);
;             PG8_WAIT_V(8); PG8_WAIT_L(0); PG8_BAR; PG8_MMA(1, 0, At, B0); PG8_MMA(1, 1, At, B1); PG8_BAR; PG8_SCHED;
.LBB11_638:
	s_add_u32 s20, s18, 0xfff80080
	s_addc_u32 s21, s19, -1
	s_add_i32 s49, 0, 0x10000
	s_cmp_eq_u32 s48, 28
	s_cselect_b32 s23, s13, s21
	s_cselect_b32 s22, s44, s20
	v_add_u32_e32 v144, s49, v147
	s_cselect_b32 s21, s11, s47
	s_cselect_b32 s20, s45, s46
	s_add_i32 s52, 0, 0x14000
	ds_read_b128 v[150:153], v144
	ds_read_b128 v[154:157], v144 offset:1024
	ds_read_b128 v[158:161], v144 offset:2048
	ds_read_b128 v[162:165], v144 offset:3072
	v_add_u32_e32 v144, s52, v147
	ds_read_b128 v[166:169], v144
	ds_read_b128 v[170:173], v144 offset:1024
	ds_read_b128 v[174:177], v144 offset:2048
	ds_read_b128 v[178:181], v144 offset:3072
	v_lshl_add_u64 v[144:145], s[18:19], 0, v[140:141]
	s_add_i32 m0, s33, 0xc000
	ds_read_b128 v[198:201], v149
	ds_read_b128 v[202:205], v149 offset:1024
	ds_read_b128 v[220:223], v149 offset:2048
	ds_read_b128 v[224:227], v149 offset:3072
	ds_read_b128 v[228:231], v149 offset:4096
	ds_read_b128 v[232:235], v149 offset:5120
	ds_read_b128 v[236:239], v149 offset:6144
	ds_read_b128 v[240:243], v149 offset:7168
	global_load_lds_dwordx4 v[144:145], off
	v_lshl_add_u64 v[144:145], s[18:19], 0, v[142:143]
	s_add_i32 m0, s33, 0xe000
	s_nop 0
	global_load_lds_dwordx4 v[144:145], off
	s_waitcnt vmcnt(8)
	s_waitcnt lgkmcnt(0)
	s_barrier
	s_setprio 1
	s_waitcnt lgkmcnt(0)
	v_mfma_f32_16x16x32_bf16 v[128:131], v[150:153], v[198:201], v[128:131]
	v_mfma_f32_16x16x32_bf16 v[128:131], v[154:157], v[202:205], v[128:131]
	v_mfma_f32_16x16x32_bf16 v[116:119], v[166:169], v[198:201], v[116:119]
	v_mfma_f32_16x16x32_bf16 v[116:119], v[170:173], v[202:205], v[116:119]
	v_mfma_f32_16x16x32_bf16 v[124:127], v[158:161], v[198:201], v[124:127]
	v_mfma_f32_16x16x32_bf16 v[124:127], v[162:165], v[202:205], v[124:127]
	v_mfma_f32_16x16x32_bf16 v[108:111], v[174:177], v[198:201], v[108:111]
	v_mfma_f32_16x16x32_bf16 v[108:111], v[178:181], v[202:205], v[108:111]
	v_mfma_f32_16x16x32_bf16 v[120:123], v[150:153], v[220:223], v[120:123]
	v_mfma_f32_16x16x32_bf16 v[120:123], v[154:157], v[224:227], v[120:123]
	v_mfma_f32_16x16x32_bf16 v[100:103], v[166:169], v[220:223], v[100:103]
	v_mfma_f32_16x16x32_bf16 v[100:103], v[170:173], v[224:227], v[100:103]
	v_mfma_f32_16x16x32_bf16 v[112:115], v[158:161], v[220:223], v[112:115]
	v_mfma_f32_16x16x32_bf16 v[112:115], v[162:165], v[224:227], v[112:115]
	v_mfma_f32_16x16x32_bf16 v[92:95], v[174:177], v[220:223], v[92:95]
	v_mfma_f32_16x16x32_bf16 v[92:95], v[178:181], v[224:227], v[92:95]
	s_setprio 0
	s_setprio 1
	v_mfma_f32_16x16x32_bf16 v[104:107], v[150:153], v[228:231], v[104:107]
	v_mfma_f32_16x16x32_bf16 v[104:107], v[154:157], v[232:235], v[104:107]
	v_mfma_f32_16x16x32_bf16 v[84:87], v[166:169], v[228:231], v[84:87]
	v_mfma_f32_16x16x32_bf16 v[84:87], v[170:173], v[232:235], v[84:87]
	v_mfma_f32_16x16x32_bf16 v[96:99], v[158:161], v[228:231], v[96:99]
	v_mfma_f32_16x16x32_bf16 v[96:99], v[162:165], v[232:235], v[96:99]
	v_mfma_f32_16x16x32_bf16 v[76:79], v[174:177], v[228:231], v[76:79]
	v_mfma_f32_16x16x32_bf16 v[76:79], v[178:181], v[232:235], v[76:79]
	v_mfma_f32_16x16x32_bf16 v[88:91], v[150:153], v[236:239], v[88:91]
	v_mfma_f32_16x16x32_bf16 v[88:91], v[154:157], v[240:243], v[88:91]
	v_mfma_f32_16x16x32_bf16 v[72:75], v[166:169], v[236:239], v[72:75]
	v_mfma_f32_16x16x32_bf16 v[72:75], v[170:173], v[240:243], v[72:75]
	v_mfma_f32_16x16x32_bf16 v[80:83], v[158:161], v[236:239], v[80:83]
	v_mfma_f32_16x16x32_bf16 v[80:83], v[162:165], v[240:243], v[80:83]
	v_mfma_f32_16x16x32_bf16 v[68:71], v[174:177], v[236:239], v[68:71]
	v_mfma_f32_16x16x32_bf16 v[68:71], v[178:181], v[240:243], v[68:71]
	s_setprio 0
	s_barrier
	s_add_i32 s49, s49, s30
	v_lshl_add_u64 v[144:145], s[20:21], 0, v[2:3]
	s_mov_b32 m0, s49
	ds_read_b128 v[198:201], v149 offset:16384
	ds_read_b128 v[202:205], v149 offset:17408
	ds_read_b128 v[220:223], v149 offset:18432
	ds_read_b128 v[224:227], v149 offset:19456
	ds_read_b128 v[228:231], v149 offset:20480
	ds_read_b128 v[232:235], v149 offset:21504
	ds_read_b128 v[236:239], v149 offset:22528
	ds_read_b128 v[240:243], v149 offset:23552
	global_load_lds_dwordx4 v[144:145], off
	s_add_i32 m0, s49, 0x2000
	s_add_u32 s50, s20, 0x80000
	v_lshl_add_u64 v[184:185], s[20:21], 0, v[132:133]
	s_addc_u32 s51, s21, 0
	s_add_i32 s49, s52, s30
	global_load_lds_dwordx4 v[184:185], off
	v_lshl_add_u64 v[186:187], s[50:51], 0, v[2:3]
	s_mov_b32 m0, s49
	v_lshl_add_u64 v[196:197], s[22:23], 0, v[134:135]
	global_load_lds_dwordx4 v[186:187], off
	v_lshl_add_u64 v[186:187], s[50:51], 0, v[132:133]
	s_add_i32 m0, s49, 0x2000
	s_nop 0
	global_load_lds_dwordx4 v[186:187], off
	v_lshl_add_u64 v[186:187], s[22:23], 0, v[136:137]
	s_mov_b32 m0, s33
	s_nop 0
	global_load_lds_dwordx4 v[186:187], off
	s_mov_b32 m0, s36
	s_nop 0
	global_load_lds_dwordx4 v[196:197], off
	s_waitcnt vmcnt(8)
	s_waitcnt lgkmcnt(0)
	s_barrier
; #define PG8_STAGE(bufoff, gbase, voff) do { _Pragma("unroll") for (int _i = 0; _i < 2; ++_i) \
;         __builtin_amdgcn_global_load_lds((const unsigned*)((const char*)(gbase) + (voff)[_i]), (PG8_LAS unsigned*)(lds + (bufoff) + ldsw + _i * 8192), 16, 0, 0); } while (0)
; #define PG8_LDA(dst, b, h) do { _Pragma("unroll") for (int m = 0; m < 4; ++m) _Pragma("unroll") for (int k = 0; k < 2; ++k) dst[m][k] = *(const PG8_LAS bf16x8*)(lds + PG8_SA(b, h) + aoff + m * 2048 + k * 1024); } while (0)
; #define PG8_LDB(dst, b, h) do { _Pragma("unroll") for (int n = 0; n < 2; ++n) _Pragma("unroll") for (int k = 0; k < 2; ++k) dst[n][k] = *(const PG8_LAS bf16x8*)(lds + PG8_SB(b, h) + boff + n * 2048 + k * 1024); } while (0)
; #define PG8_MMA(ai, bj, At, Bt) do { __builtin_amdgcn_s_setprio(1); _Pragma("unroll") for (int m = 0; m < 4; ++m) _Pragma("unroll") for (int n = 0; n < 2; ++n) _Pragma("unroll") for (int k = 0; k < 2; ++k) \
;         acc[ai][bj][m][n] = __builtin_amdgcn_mfma_f32_16x16x32_bf16(Bt[n][k], At[m][k], acc[ai][bj][m][n], 0, 0, 0); __builtin_amdgcn_s_setprio(0); } while (0)
; #define PG8_WAIT_V(n) asm volatile("s_waitcnt vmcnt(" #n ")" ::: "memory")
; #define PG8_WAIT_L(n) asm volatile("s_waitcnt lgkmcnt(" #n ")" ::: "memory")
; #define PG8_BAR __builtin_amdgcn_s_barrier()
; #define PG8_SCHED __builtin_amdgcn_sched_barrier(0)
; template <class Epi, class Sched, bool ALIGN_EPI = false, bool SP2 = false>
; __device__ __forceinline__ void gemm_phase(PG8_LAS unsigned char* lds, const Gemm g, const Sched& S, const Epi& E) {
;     ...
;             PG8_WAIT_V(8); PG8_WAIT_L(0); PG8_BAR; PG8_MMA(1, 0, At, B0); PG8_MMA(1, 1, At, B1); PG8_BAR; PG8_SCHED;
;             PG8_LDB(B0, 1, 0); PG8_LDB(B1, 1, 1); PG8_SCHED; PG8_LDA(At, 1, 0); PG8_STAGE(PG8_SA(0, 1), a2 + hstep, voffA);
;             PG8_WAIT_V(8); PG8_WAIT_L(0); PG8_BAR; PG8_MMA(0, 0, At, B0); PG8_MMA(0, 1, At, B1); PG8_BAR; PG8_SCHED;
	s_setprio 1
	s_waitcnt lgkmcnt(0)
	v_mfma_f32_16x16x32_bf16 v[64:67], v[150:153], v[198:201], v[64:67]
	v_mfma_f32_16x16x32_bf16 v[64:67], v[154:157], v[202:205], v[64:67]
	v_mfma_f32_16x16x32_bf16 v[52:55], v[166:169], v[198:201], v[52:55]
	v_mfma_f32_16x16x32_bf16 v[52:55], v[170:173], v[202:205], v[52:55]
	v_mfma_f32_16x16x32_bf16 v[60:63], v[158:161], v[198:201], v[60:63]
	v_mfma_f32_16x16x32_bf16 v[60:63], v[162:165], v[202:205], v[60:63]
	v_mfma_f32_16x16x32_bf16 v[44:47], v[174:177], v[198:201], v[44:47]
	v_mfma_f32_16x16x32_bf16 v[44:47], v[178:181], v[202:205], v[44:47]
	v_mfma_f32_16x16x32_bf16 v[56:59], v[150:153], v[220:223], v[56:59]
	v_mfma_f32_16x16x32_bf16 v[56:59], v[154:157], v[224:227], v[56:59]
	v_mfma_f32_16x16x32_bf16 v[36:39], v[166:169], v[220:223], v[36:39]
	v_mfma_f32_16x16x32_bf16 v[36:39], v[170:173], v[224:227], v[36:39]
	v_mfma_f32_16x16x32_bf16 v[48:51], v[158:161], v[220:223], v[48:51]
	v_mfma_f32_16x16x32_bf16 v[48:51], v[162:165], v[224:227], v[48:51]
	v_mfma_f32_16x16x32_bf16 v[28:31], v[174:177], v[220:223], v[28:31]
	v_mfma_f32_16x16x32_bf16 v[28:31], v[178:181], v[224:227], v[28:31]
	s_setprio 0
	s_setprio 1
	v_mfma_f32_16x16x32_bf16 v[40:43], v[150:153], v[228:231], v[40:43]
	v_mfma_f32_16x16x32_bf16 v[40:43], v[154:157], v[232:235], v[40:43]
	v_mfma_f32_16x16x32_bf16 v[20:23], v[166:169], v[228:231], v[20:23]
	v_mfma_f32_16x16x32_bf16 v[20:23], v[170:173], v[232:235], v[20:23]
	v_mfma_f32_16x16x32_bf16 v[32:35], v[158:161], v[228:231], v[32:35]
	v_mfma_f32_16x16x32_bf16 v[32:35], v[162:165], v[232:235], v[32:35]
	v_mfma_f32_16x16x32_bf16 v[12:15], v[174:177], v[228:231], v[12:15]
	v_mfma_f32_16x16x32_bf16 v[12:15], v[178:181], v[232:235], v[12:15]
	v_mfma_f32_16x16x32_bf16 v[24:27], v[150:153], v[236:239], v[24:27]
	v_mfma_f32_16x16x32_bf16 v[24:27], v[154:157], v[240:243], v[24:27]
	v_mfma_f32_16x16x32_bf16 v[8:11], v[166:169], v[236:239], v[8:11]
	v_mfma_f32_16x16x32_bf16 v[8:11], v[170:173], v[240:243], v[8:11]
	v_mfma_f32_16x16x32_bf16 v[16:19], v[158:161], v[236:239], v[16:19]
	v_mfma_f32_16x16x32_bf16 v[16:19], v[162:165], v[240:243], v[16:19]
	v_mfma_f32_16x16x32_bf16 v[4:7], v[174:177], v[236:239], v[4:7]
	v_mfma_f32_16x16x32_bf16 v[4:7], v[178:181], v[240:243], v[4:7]
	s_setprio 0
	s_barrier
	s_add_i32 s49, 0, 0x18000
	s_add_i32 s50, 0, 0x1c000
	v_add_u32_e32 v162, s49, v147
	v_add_u32_e32 v178, s50, v147
	ds_read_b128 v[150:153], v162
	ds_read_b128 v[154:157], v162 offset:1024
	ds_read_b128 v[158:161], v162 offset:2048
	ds_read_b128 v[162:165], v162 offset:3072
	ds_read_b128 v[166:169], v178
	ds_read_b128 v[170:173], v178 offset:1024
	ds_read_b128 v[174:177], v178 offset:2048
	ds_read_b128 v[178:181], v178 offset:3072
	s_add_u32 s22, s22, 0x80000
	s_addc_u32 s23, s23, 0
	s_mov_b32 m0, s37
	v_lshl_add_u64 v[206:207], s[22:23], 0, v[136:137]
	ds_read_b128 v[198:201], v149 offset:32768
	ds_read_b128 v[202:205], v149 offset:33792
	ds_read_b128 v[220:223], v149 offset:34816
	ds_read_b128 v[224:227], v149 offset:35840
	ds_read_b128 v[228:231], v149 offset:36864
	ds_read_b128 v[232:235], v149 offset:37888
	ds_read_b128 v[236:239], v149 offset:38912
	ds_read_b128 v[240:243], v149 offset:39936
	global_load_lds_dwordx4 v[206:207], off
	v_lshl_add_u64 v[206:207], s[22:23], 0, v[134:135]
	s_mov_b32 m0, s38
	s_nop 0
	global_load_lds_dwordx4 v[206:207], off
	s_waitcnt vmcnt(8)
	s_waitcnt lgkmcnt(0)
	s_barrier
	s_setprio 1
	s_waitcnt lgkmcnt(0)
	v_mfma_f32_16x16x32_bf16 v[128:131], v[150:153], v[198:201], v[128:131]
	v_mfma_f32_16x16x32_bf16 v[128:131], v[154:157], v[202:205], v[128:131]
	v_mfma_f32_16x16x32_bf16 v[116:119], v[166:169], v[198:201], v[116:119]
	v_mfma_f32_16x16x32_bf16 v[116:119], v[170:173], v[202:205], v[116:119]
	v_mfma_f32_16x16x32_bf16 v[124:127], v[158:161], v[198:201], v[124:127]
	v_mfma_f32_16x16x32_bf16 v[124:127], v[162:165], v[202:205], v[124:127]
	v_mfma_f32_16x16x32_bf16 v[108:111], v[174:177], v[198:201], v[108:111]
	v_mfma_f32_16x16x32_bf16 v[108:111], v[178:181], v[202:205], v[108:111]
	v_mfma_f32_16x16x32_bf16 v[120:123], v[150:153], v[220:223], v[120:123]
	v_mfma_f32_16x16x32_bf16 v[120:123], v[154:157], v[224:227], v[120:123]
	v_mfma_f32_16x16x32_bf16 v[100:103], v[166:169], v[220:223], v[100:103]
	v_mfma_f32_16x16x32_bf16 v[100:103], v[170:173], v[224:227], v[100:103]
	v_mfma_f32_16x16x32_bf16 v[112:115], v[158:161], v[220:223], v[112:115]
	v_mfma_f32_16x16x32_bf16 v[112:115], v[162:165], v[224:227], v[112:115]
	v_mfma_f32_16x16x32_bf16 v[92:95], v[174:177], v[220:223], v[92:95]
	v_mfma_f32_16x16x32_bf16 v[92:95], v[178:181], v[224:227], v[92:95]
	s_setprio 0
	s_setprio 1
	v_mfma_f32_16x16x32_bf16 v[104:107], v[150:153], v[228:231], v[104:107]
	v_mfma_f32_16x16x32_bf16 v[104:107], v[154:157], v[232:235], v[104:107]
	v_mfma_f32_16x16x32_bf16 v[84:87], v[166:169], v[228:231], v[84:87]
	v_mfma_f32_16x16x32_bf16 v[84:87], v[170:173], v[232:235], v[84:87]
	v_mfma_f32_16x16x32_bf16 v[96:99], v[158:161], v[228:231], v[96:99]
	v_mfma_f32_16x16x32_bf16 v[96:99], v[162:165], v[232:235], v[96:99]
	v_mfma_f32_16x16x32_bf16 v[76:79], v[174:177], v[228:231], v[76:79]
	v_mfma_f32_16x16x32_bf16 v[76:79], v[178:181], v[232:235], v[76:79]
	v_mfma_f32_16x16x32_bf16 v[88:91], v[150:153], v[236:239], v[88:91]
	v_mfma_f32_16x16x32_bf16 v[88:91], v[154:157], v[240:243], v[88:91]
	v_mfma_f32_16x16x32_bf16 v[72:75], v[166:169], v[236:239], v[72:75]
	v_mfma_f32_16x16x32_bf16 v[72:75], v[170:173], v[240:243], v[72:75]
	v_mfma_f32_16x16x32_bf16 v[80:83], v[158:161], v[236:239], v[80:83]
	v_mfma_f32_16x16x32_bf16 v[80:83], v[162:165], v[240:243], v[80:83]
	v_mfma_f32_16x16x32_bf16 v[68:71], v[174:177], v[236:239], v[68:71]
	v_mfma_f32_16x16x32_bf16 v[68:71], v[178:181], v[240:243], v[68:71]
	s_setprio 0
	s_barrier
; #define PG8_STAGE(bufoff, gbase, voff) do { _Pragma("unroll") for (int _i = 0; _i < 2; ++_i) \
;         __builtin_amdgcn_global_load_lds((const unsigned*)((const char*)(gbase) + (voff)[_i]), (PG8_LAS unsigned*)(lds + (bufoff) + ldsw + _i * 8192), 16, 0, 0); } while (0)
; #define PG8_LDA(dst, b, h) do { _Pragma("unroll") for (int m = 0; m < 4; ++m) _Pragma("unroll") for (int k = 0; k < 2; ++k) dst[m][k] = *(const PG8_LAS bf16x8*)(lds + PG8_SA(b, h) + aoff + m * 2048 + k * 1024); } while (0)
; #define PG8_MMA(ai, bj, At, Bt) do { __builtin_amdgcn_s_setprio(1); _Pragma("unroll") for (int m = 0; m < 4; ++m) _Pragma("unroll") for (int n = 0; n < 2; ++n) _Pragma("unroll") for (int k = 0; k < 2; ++k) \
;         acc[ai][bj][m][n] = __builtin_amdgcn_mfma_f32_16x16x32_bf16(Bt[n][k], At[m][k], acc[ai][bj][m][n], 0, 0, 0); __builtin_amdgcn_s_setprio(0); } while (0)
; #define PG8_WAIT_V(n) asm volatile("s_waitcnt vmcnt(" #n ")" ::: "memory")
; #define PG8_WAIT_L(n) asm volatile("s_waitcnt lgkmcnt(" #n ")" ::: "memory")
; #define PG8_BAR __builtin_amdgcn_s_barrier()
; #define PG8_SCHED __builtin_amdgcn_sched_barrier(0)
; template <class Epi, class Sched, bool ALIGN_EPI = false, bool SP2 = false>
; __device__ __forceinline__ void gemm_phase(PG8_LAS unsigned char* lds, const Gemm g, const Sched& S, const Epi& E) {
;     ...
;         for (int t = 0; t < nt; t += 2) {
;     ...
;             PG8_LDA(At, 1, 1); PG8_STAGE(PG8_SB(1, 0), b3, voffB); PG8_STAGE(PG8_SB(1, 1), b3 + hstep, voffB); PG8_STAGE(PG8_SA(1, 0), a3, voffA);
;             PG8_WAIT_V(8); PG8_WAIT_L(0); PG8_BAR; PG8_MMA(1, 0, At, B0); PG8_MMA(1, 1, At, B1); PG8_BAR; PG8_SCHED;
	s_add_i32 s22, s49, s30
	v_lshl_add_u64 v[144:145], v[144:145], 0, s[34:35]
	s_mov_b32 m0, s22
	ds_read_b128 v[198:201], v149 offset:49152
	ds_read_b128 v[202:205], v149 offset:50176
	ds_read_b128 v[220:223], v149 offset:51200
	ds_read_b128 v[224:227], v149 offset:52224
	ds_read_b128 v[228:231], v149 offset:53248
	ds_read_b128 v[232:235], v149 offset:54272
	ds_read_b128 v[236:239], v149 offset:55296
	ds_read_b128 v[240:243], v149 offset:56320
	global_load_lds_dwordx4 v[144:145], off
	s_add_i32 m0, s22, 0x2000
	s_add_u32 s20, s20, 0x80080
	v_lshl_add_u64 v[144:145], v[184:185], 0, s[34:35]
	s_addc_u32 s21, s21, 0
	s_add_i32 s22, s50, s30
	global_load_lds_dwordx4 v[144:145], off
	v_lshl_add_u64 v[144:145], s[20:21], 0, v[2:3]
	s_mov_b32 m0, s22
	s_nop 0
	global_load_lds_dwordx4 v[144:145], off
	v_lshl_add_u64 v[144:145], s[20:21], 0, v[132:133]
	s_add_i32 m0, s22, 0x2000
	s_nop 0
	global_load_lds_dwordx4 v[144:145], off
	v_lshl_add_u64 v[144:145], v[186:187], 0, s[34:35]
	s_mov_b32 m0, s39
	s_nop 0
	global_load_lds_dwordx4 v[144:145], off
	v_lshl_add_u64 v[144:145], v[196:197], 0, s[34:35]
	s_mov_b32 m0, s40
	s_nop 0
	global_load_lds_dwordx4 v[144:145], off
	s_waitcnt vmcnt(8)
	s_waitcnt lgkmcnt(0)
	s_barrier
	s_setprio 1
	s_waitcnt lgkmcnt(0)
	v_mfma_f32_16x16x32_bf16 v[64:67], v[150:153], v[198:201], v[64:67]
	v_mfma_f32_16x16x32_bf16 v[64:67], v[154:157], v[202:205], v[64:67]
	v_mfma_f32_16x16x32_bf16 v[52:55], v[166:169], v[198:201], v[52:55]
	v_mfma_f32_16x16x32_bf16 v[52:55], v[170:173], v[202:205], v[52:55]
	v_mfma_f32_16x16x32_bf16 v[60:63], v[158:161], v[198:201], v[60:63]
	v_mfma_f32_16x16x32_bf16 v[60:63], v[162:165], v[202:205], v[60:63]
	v_mfma_f32_16x16x32_bf16 v[44:47], v[174:177], v[198:201], v[44:47]
	v_mfma_f32_16x16x32_bf16 v[44:47], v[178:181], v[202:205], v[44:47]
	v_mfma_f32_16x16x32_bf16 v[56:59], v[150:153], v[220:223], v[56:59]
	v_mfma_f32_16x16x32_bf16 v[56:59], v[154:157], v[224:227], v[56:59]
	v_mfma_f32_16x16x32_bf16 v[36:39], v[166:169], v[220:223], v[36:39]
	v_mfma_f32_16x16x32_bf16 v[36:39], v[170:173], v[224:227], v[36:39]
	v_mfma_f32_16x16x32_bf16 v[48:51], v[158:161], v[220:223], v[48:51]
	v_mfma_f32_16x16x32_bf16 v[48:51], v[162:165], v[224:227], v[48:51]
	v_mfma_f32_16x16x32_bf16 v[28:31], v[174:177], v[220:223], v[28:31]
	v_mfma_f32_16x16x32_bf16 v[28:31], v[178:181], v[224:227], v[28:31]
	s_setprio 0
	s_setprio 1
	v_mfma_f32_16x16x32_bf16 v[40:43], v[150:153], v[228:231], v[40:43]
	v_mfma_f32_16x16x32_bf16 v[40:43], v[154:157], v[232:235], v[40:43]
	v_mfma_f32_16x16x32_bf16 v[20:23], v[166:169], v[228:231], v[20:23]
	v_mfma_f32_16x16x32_bf16 v[20:23], v[170:173], v[232:235], v[20:23]
	v_mfma_f32_16x16x32_bf16 v[32:35], v[158:161], v[228:231], v[32:35]
	v_mfma_f32_16x16x32_bf16 v[32:35], v[162:165], v[232:235], v[32:35]
	v_mfma_f32_16x16x32_bf16 v[12:15], v[174:177], v[228:231], v[12:15]
	v_mfma_f32_16x16x32_bf16 v[12:15], v[178:181], v[232:235], v[12:15]
	v_mfma_f32_16x16x32_bf16 v[24:27], v[150:153], v[236:239], v[24:27]
	v_mfma_f32_16x16x32_bf16 v[24:27], v[154:157], v[240:243], v[24:27]
	v_mfma_f32_16x16x32_bf16 v[8:11], v[166:169], v[236:239], v[8:11]
	v_mfma_f32_16x16x32_bf16 v[8:11], v[170:173], v[240:243], v[8:11]
	v_mfma_f32_16x16x32_bf16 v[16:19], v[158:161], v[236:239], v[16:19]
	v_mfma_f32_16x16x32_bf16 v[16:19], v[162:165], v[240:243], v[16:19]
	v_mfma_f32_16x16x32_bf16 v[4:7], v[174:177], v[236:239], v[4:7]
	v_mfma_f32_16x16x32_bf16 v[4:7], v[178:181], v[240:243], v[4:7]
	s_setprio 0
	s_barrier
	s_add_i32 s48, s48, 2
	s_add_u32 s18, s18, 0x100
	s_addc_u32 s19, s19, 0
	s_add_u32 s46, s46, 0x100
	s_addc_u32 s47, s47, 0
	s_cmp_gt_u32 s48, 29
	s_cbranch_scc0 .LBB11_638
	s_and_b64 vcc, exec, s[4:5]
	s_cbranch_vccz .LBB11_641
	s_barrier

; #define PG8_STAGE(bufoff, gbase, voff) do { _Pragma("unroll") for (int _i = 0; _i < 2; ++_i) \
;         __builtin_amdgcn_global_load_lds((const unsigned*)((const char*)(gbase) + (voff)[_i]), (PG8_LAS unsigned*)(lds + (bufoff) + ldsw + _i * 8192), 16, 0, 0); } while (0)
; #define PG8_LDA(dst, b, h) do { _Pragma("unroll") for (int m = 0; m < 4; ++m) _Pragma("unroll") for (int k = 0; k < 2; ++k) dst[m][k] = *(const PG8_LAS bf16x8*)(lds + PG8_SA(b, h) + aoff + m * 2048 + k * 1024); } while (0)
; #define PG8_LDB(dst, b, h) do { _Pragma("unroll") for (int n = 0; n < 2; ++n) _Pragma("unroll") for (int k = 0; k < 2; ++k) dst[n][k] = *(const PG8_LAS bf16x8*)(lds + PG8_SB(b, h) + boff + n * 2048 + k * 1024); } while (0)
; #define PG8_MMA(ai, bj, At, Bt) do { __builtin_amdgcn_s_setprio(1); _Pragma("unroll") for (int m = 0; m < 4; ++m) _Pragma("unroll") for (int n = 0; n < 2; ++n) _Pragma("unroll") for (int k = 0; k < 2; ++k) \
;         acc[ai][bj][m][n] = __builtin_amdgcn_mfma_f32_16x16x32_bf16(Bt[n][k], At[m][k], acc[ai][bj][m][n], 0, 0, 0); __builtin_amdgcn_s_setprio(0); } while (0)
; #define PG8_WAIT_V(n) asm volatile("s_waitcnt vmcnt(" #n ")" ::: "memory")
; #define PG8_WAIT_L(n) asm volatile("s_waitcnt lgkmcnt(" #n ")" ::: "memory")
; template <class Epi, class Sched, bool ALIGN_EPI = false, bool SP2 = false>
; __device__ __forceinline__ void gemm_phase(PG8_LAS unsigned char* lds, const Gemm g, const Sched& S, const Epi& E) {
;     ...
;             const bool last = (t == nt - 2);
;             const char* a1 = cA + (size_t)(t + 1) * kstep;
;             const char* a2 = last ? nA : cA + (size_t)(t + 2) * kstep; const char* b2 = last ? nB : cB + (size_t)(t + 2) * kstep;
;             const char* a3 = a2 + kstep; const char* b3 = b2 + kstep;
;             if (last && has_next) S.a_ready(nxt);
;             if constexpr (SP2) {
;             PG8_LDB(B0, 0, 0); PG8_LDB(B1, 0, 1); PG8_SCHED; PG8_LDA(At, 0, 0); PG8_STAGE(PG8_SA(1, 1), a1 + hstep, voffA);
;             PG8_WAIT_V(8); PG8_WAIT_L(0); PG8_BAR; PG8_MMA(0, 0, At, B0); PG8_MMA(0, 1, At, B1); PG8_BAR; PG8_SCHED;
;             PG8_LDA(At, 0, 1); PG8_STAGE(PG8_SB(0, 0), b2, voffB); PG8_STAGE(PG8_SB(0, 1), b2 + hstep, voffB); PG8_STAGE(PG8_SA(0, 0), a2, voffA);
;             PG8_WAIT_V(8); PG8_WAIT_L(0); PG8_BAR; PG8_MMA(1, 0, At, B0); PG8_MMA(1, 1, At, B1); PG8_BAR; PG8_SCHED;
.LBB11_913:
	s_add_u32 s16, s14, 0xfff80080
	s_addc_u32 s17, s15, -1
	s_add_i32 s44, 0, 0x10000
	s_cmp_eq_u32 s43, 28
	s_cselect_b32 s19, s9, s17
	s_cselect_b32 s18, s37, s16
	v_add_u32_e32 v144, s44, v146
	s_cselect_b32 s17, s7, s42
	s_cselect_b32 s16, s40, s41
	s_add_i32 s46, 0, 0x14000
	ds_read_b128 v[150:153], v144
	ds_read_b128 v[154:157], v144 offset:1024
	ds_read_b128 v[158:161], v144 offset:2048
	ds_read_b128 v[162:165], v144 offset:3072
	v_add_u32_e32 v144, s46, v146
	ds_read_b128 v[166:169], v144
	ds_read_b128 v[170:173], v144 offset:1024
	ds_read_b128 v[174:177], v144 offset:2048
	ds_read_b128 v[178:181], v144 offset:3072
	v_lshl_add_u64 v[144:145], s[14:15], 0, v[140:141]
	s_add_i32 m0, s24, 0xc000
	ds_read_b128 v[198:201], v148
	ds_read_b128 v[202:205], v148 offset:1024
	ds_read_b128 v[220:223], v148 offset:2048
	ds_read_b128 v[224:227], v148 offset:3072
	ds_read_b128 v[228:231], v148 offset:4096
	ds_read_b128 v[232:235], v148 offset:5120
	ds_read_b128 v[236:239], v148 offset:6144
	ds_read_b128 v[240:243], v148 offset:7168
	global_load_lds_dwordx4 v[144:145], off
	v_lshl_add_u64 v[144:145], s[14:15], 0, v[142:143]
	s_add_i32 m0, s24, 0xe000
	s_nop 0
	global_load_lds_dwordx4 v[144:145], off
	s_waitcnt vmcnt(8)
	s_waitcnt lgkmcnt(0)
	s_barrier
	s_setprio 1
	s_waitcnt lgkmcnt(0)
	v_mfma_f32_16x16x32_bf16 v[128:131], v[150:153], v[198:201], v[128:131]
	v_mfma_f32_16x16x32_bf16 v[128:131], v[154:157], v[202:205], v[128:131]
	v_mfma_f32_16x16x32_bf16 v[116:119], v[166:169], v[198:201], v[116:119]
	v_mfma_f32_16x16x32_bf16 v[116:119], v[170:173], v[202:205], v[116:119]
	v_mfma_f32_16x16x32_bf16 v[124:127], v[158:161], v[198:201], v[124:127]
	v_mfma_f32_16x16x32_bf16 v[124:127], v[162:165], v[202:205], v[124:127]
	v_mfma_f32_16x16x32_bf16 v[108:111], v[174:177], v[198:201], v[108:111]
	v_mfma_f32_16x16x32_bf16 v[108:111], v[178:181], v[202:205], v[108:111]
	v_mfma_f32_16x16x32_bf16 v[120:123], v[150:153], v[220:223], v[120:123]
	v_mfma_f32_16x16x32_bf16 v[120:123], v[154:157], v[224:227], v[120:123]
	v_mfma_f32_16x16x32_bf16 v[100:103], v[166:169], v[220:223], v[100:103]
	v_mfma_f32_16x16x32_bf16 v[100:103], v[170:173], v[224:227], v[100:103]
	v_mfma_f32_16x16x32_bf16 v[112:115], v[158:161], v[220:223], v[112:115]
	v_mfma_f32_16x16x32_bf16 v[112:115], v[162:165], v[224:227], v[112:115]
	v_mfma_f32_16x16x32_bf16 v[92:95], v[174:177], v[220:223], v[92:95]
	v_mfma_f32_16x16x32_bf16 v[92:95], v[178:181], v[224:227], v[92:95]
	s_setprio 0
	s_setprio 1
	v_mfma_f32_16x16x32_bf16 v[104:107], v[150:153], v[228:231], v[104:107]
	v_mfma_f32_16x16x32_bf16 v[104:107], v[154:157], v[232:235], v[104:107]
	v_mfma_f32_16x16x32_bf16 v[84:87], v[166:169], v[228:231], v[84:87]
	v_mfma_f32_16x16x32_bf16 v[84:87], v[170:173], v[232:235], v[84:87]
	v_mfma_f32_16x16x32_bf16 v[96:99], v[158:161], v[228:231], v[96:99]
	v_mfma_f32_16x16x32_bf16 v[96:99], v[162:165], v[232:235], v[96:99]
	v_mfma_f32_16x16x32_bf16 v[76:79], v[174:177], v[228:231], v[76:79]
	v_mfma_f32_16x16x32_bf16 v[76:79], v[178:181], v[232:235], v[76:79]
	v_mfma_f32_16x16x32_bf16 v[88:91], v[150:153], v[236:239], v[88:91]
	v_mfma_f32_16x16x32_bf16 v[88:91], v[154:157], v[240:243], v[88:91]
	v_mfma_f32_16x16x32_bf16 v[72:75], v[166:169], v[236:239], v[72:75]
	v_mfma_f32_16x16x32_bf16 v[72:75], v[170:173], v[240:243], v[72:75]
	v_mfma_f32_16x16x32_bf16 v[80:83], v[158:161], v[236:239], v[80:83]
	v_mfma_f32_16x16x32_bf16 v[80:83], v[162:165], v[240:243], v[80:83]
	v_mfma_f32_16x16x32_bf16 v[68:71], v[174:177], v[236:239], v[68:71]
	v_mfma_f32_16x16x32_bf16 v[68:71], v[178:181], v[240:243], v[68:71]
	s_setprio 0
	s_barrier
	s_add_i32 s44, s44, s23
	v_lshl_add_u64 v[144:145], s[16:17], 0, v[2:3]
	s_mov_b32 m0, s44
	ds_read_b128 v[198:201], v148 offset:16384
	ds_read_b128 v[202:205], v148 offset:17408
	ds_read_b128 v[220:223], v148 offset:18432
	ds_read_b128 v[224:227], v148 offset:19456
	ds_read_b128 v[228:231], v148 offset:20480
	ds_read_b128 v[232:235], v148 offset:21504
	ds_read_b128 v[236:239], v148 offset:22528
	ds_read_b128 v[240:243], v148 offset:23552
	global_load_lds_dwordx4 v[144:145], off
	s_add_i32 m0, s44, 0x2000
	s_add_u32 s44, s16, 0x80000
	v_lshl_add_u64 v[184:185], s[16:17], 0, v[132:133]
	s_addc_u32 s45, s17, 0
	s_add_i32 s46, s46, s23
	global_load_lds_dwordx4 v[184:185], off
	v_lshl_add_u64 v[186:187], s[44:45], 0, v[2:3]
	s_mov_b32 m0, s46
	v_lshl_add_u64 v[196:197], s[18:19], 0, v[134:135]
	global_load_lds_dwordx4 v[186:187], off
	v_lshl_add_u64 v[186:187], s[44:45], 0, v[132:133]
	s_add_i32 m0, s46, 0x2000
	s_nop 0
	global_load_lds_dwordx4 v[186:187], off
	v_lshl_add_u64 v[186:187], s[18:19], 0, v[136:137]
	s_mov_b32 m0, s24
	s_nop 0
	global_load_lds_dwordx4 v[186:187], off
	s_mov_b32 m0, s25
	s_nop 0
	global_load_lds_dwordx4 v[196:197], off
	s_waitcnt vmcnt(8)
	s_waitcnt lgkmcnt(0)
	s_barrier
; #define PG8_STAGE(bufoff, gbase, voff) do { _Pragma("unroll") for (int _i = 0; _i < 2; ++_i) \
;         __builtin_amdgcn_global_load_lds((const unsigned*)((const char*)(gbase) + (voff)[_i]), (PG8_LAS unsigned*)(lds + (bufoff) + ldsw + _i * 8192), 16, 0, 0); } while (0)
; #define PG8_LDA(dst, b, h) do { _Pragma("unroll") for (int m = 0; m < 4; ++m) _Pragma("unroll") for (int k = 0; k < 2; ++k) dst[m][k] = *(const PG8_LAS bf16x8*)(lds + PG8_SA(b, h) + aoff + m * 2048 + k * 1024); } while (0)
; #define PG8_LDB(dst, b, h) do { _Pragma("unroll") for (int n = 0; n < 2; ++n) _Pragma("unroll") for (int k = 0; k < 2; ++k) dst[n][k] = *(const PG8_LAS bf16x8*)(lds + PG8_SB(b, h) + boff + n * 2048 + k * 1024); } while (0)
; #define PG8_MMA(ai, bj, At, Bt) do { __builtin_amdgcn_s_setprio(1); _Pragma("unroll") for (int m = 0; m < 4; ++m) _Pragma("unroll") for (int n = 0; n < 2; ++n) _Pragma("unroll") for (int k = 0; k < 2; ++k) \
;         acc[ai][bj][m][n] = __builtin_amdgcn_mfma_f32_16x16x32_bf16(Bt[n][k], At[m][k], acc[ai][bj][m][n], 0, 0, 0); __builtin_amdgcn_s_setprio(0); } while (0)
; #define PG8_WAIT_V(n) asm volatile("s_waitcnt vmcnt(" #n ")" ::: "memory")
; #define PG8_WAIT_L(n) asm volatile("s_waitcnt lgkmcnt(" #n ")" ::: "memory")
; #define PG8_BAR __builtin_amdgcn_s_barrier()
; #define PG8_SCHED __builtin_amdgcn_sched_barrier(0)
; template <class Epi, class Sched, bool ALIGN_EPI = false, bool SP2 = false>
; __device__ __forceinline__ void gemm_phase(PG8_LAS unsigned char* lds, const Gemm g, const Sched& S, const Epi& E) {
;     ...
;             PG8_WAIT_V(8); PG8_WAIT_L(0); PG8_BAR; PG8_MMA(1, 0, At, B0); PG8_MMA(1, 1, At, B1); PG8_BAR; PG8_SCHED;
;             PG8_LDB(B0, 1, 0); PG8_LDB(B1, 1, 1); PG8_SCHED; PG8_LDA(At, 1, 0); PG8_STAGE(PG8_SA(0, 1), a2 + hstep, voffA);
;             PG8_WAIT_V(8); PG8_WAIT_L(0); PG8_BAR; PG8_MMA(0, 0, At, B0); PG8_MMA(0, 1, At, B1); PG8_BAR; PG8_SCHED;
	s_setprio 1
	s_waitcnt lgkmcnt(0)
	v_mfma_f32_16x16x32_bf16 v[64:67], v[150:153], v[198:201], v[64:67]
	v_mfma_f32_16x16x32_bf16 v[64:67], v[154:157], v[202:205], v[64:67]
	v_mfma_f32_16x16x32_bf16 v[52:55], v[166:169], v[198:201], v[52:55]
	v_mfma_f32_16x16x32_bf16 v[52:55], v[170:173], v[202:205], v[52:55]
	v_mfma_f32_16x16x32_bf16 v[60:63], v[158:161], v[198:201], v[60:63]
	v_mfma_f32_16x16x32_bf16 v[60:63], v[162:165], v[202:205], v[60:63]
	v_mfma_f32_16x16x32_bf16 v[44:47], v[174:177], v[198:201], v[44:47]
	v_mfma_f32_16x16x32_bf16 v[44:47], v[178:181], v[202:205], v[44:47]
	v_mfma_f32_16x16x32_bf16 v[56:59], v[150:153], v[220:223], v[56:59]
	v_mfma_f32_16x16x32_bf16 v[56:59], v[154:157], v[224:227], v[56:59]
	v_mfma_f32_16x16x32_bf16 v[36:39], v[166:169], v[220:223], v[36:39]
	v_mfma_f32_16x16x32_bf16 v[36:39], v[170:173], v[224:227], v[36:39]
	v_mfma_f32_16x16x32_bf16 v[48:51], v[158:161], v[220:223], v[48:51]
	v_mfma_f32_16x16x32_bf16 v[48:51], v[162:165], v[224:227], v[48:51]
	v_mfma_f32_16x16x32_bf16 v[28:31], v[174:177], v[220:223], v[28:31]
	v_mfma_f32_16x16x32_bf16 v[28:31], v[178:181], v[224:227], v[28:31]
	s_setprio 0
	s_setprio 1
	v_mfma_f32_16x16x32_bf16 v[40:43], v[150:153], v[228:231], v[40:43]
	v_mfma_f32_16x16x32_bf16 v[40:43], v[154:157], v[232:235], v[40:43]
	v_mfma_f32_16x16x32_bf16 v[20:23], v[166:169], v[228:231], v[20:23]
	v_mfma_f32_16x16x32_bf16 v[20:23], v[170:173], v[232:235], v[20:23]
	v_mfma_f32_16x16x32_bf16 v[32:35], v[158:161], v[228:231], v[32:35]
	v_mfma_f32_16x16x32_bf16 v[32:35], v[162:165], v[232:235], v[32:35]
	v_mfma_f32_16x16x32_bf16 v[12:15], v[174:177], v[228:231], v[12:15]
	v_mfma_f32_16x16x32_bf16 v[12:15], v[178:181], v[232:235], v[12:15]
	v_mfma_f32_16x16x32_bf16 v[24:27], v[150:153], v[236:239], v[24:27]
	v_mfma_f32_16x16x32_bf16 v[24:27], v[154:157], v[240:243], v[24:27]
	v_mfma_f32_16x16x32_bf16 v[8:11], v[166:169], v[236:239], v[8:11]
	v_mfma_f32_16x16x32_bf16 v[8:11], v[170:173], v[240:243], v[8:11]
	v_mfma_f32_16x16x32_bf16 v[16:19], v[158:161], v[236:239], v[16:19]
	v_mfma_f32_16x16x32_bf16 v[16:19], v[162:165], v[240:243], v[16:19]
	v_mfma_f32_16x16x32_bf16 v[4:7], v[174:177], v[236:239], v[4:7]
	v_mfma_f32_16x16x32_bf16 v[4:7], v[178:181], v[240:243], v[4:7]
	s_setprio 0
	s_barrier
	s_add_i32 s44, 0, 0x18000
	v_add_u32_e32 v149, s44, v146
	s_add_i32 s45, 0, 0x1c000
	ds_read_b128 v[150:153], v149
	ds_read_b128 v[154:157], v149 offset:1024
	ds_read_b128 v[158:161], v149 offset:2048
	ds_read_b128 v[162:165], v149 offset:3072
	v_add_u32_e32 v149, s45, v146
	ds_read_b128 v[166:169], v149
	ds_read_b128 v[170:173], v149 offset:1024
	ds_read_b128 v[174:177], v149 offset:2048
	ds_read_b128 v[178:181], v149 offset:3072
	s_add_u32 s18, s18, 0x80000
	s_addc_u32 s19, s19, 0
	s_mov_b32 m0, s26
	v_lshl_add_u64 v[206:207], s[18:19], 0, v[136:137]
	ds_read_b128 v[198:201], v148 offset:32768
	ds_read_b128 v[202:205], v148 offset:33792
	ds_read_b128 v[220:223], v148 offset:34816
	ds_read_b128 v[224:227], v148 offset:35840
	ds_read_b128 v[228:231], v148 offset:36864
	ds_read_b128 v[232:235], v148 offset:37888
	ds_read_b128 v[236:239], v148 offset:38912
	ds_read_b128 v[240:243], v148 offset:39936
	global_load_lds_dwordx4 v[206:207], off
	v_lshl_add_u64 v[206:207], s[18:19], 0, v[134:135]
	s_mov_b32 m0, s27
	s_nop 0
	global_load_lds_dwordx4 v[206:207], off
	s_waitcnt vmcnt(8)
	s_waitcnt lgkmcnt(0)
	s_barrier
	s_setprio 1
	s_waitcnt lgkmcnt(0)
	v_mfma_f32_16x16x32_bf16 v[128:131], v[150:153], v[198:201], v[128:131]
	v_mfma_f32_16x16x32_bf16 v[128:131], v[154:157], v[202:205], v[128:131]
	v_mfma_f32_16x16x32_bf16 v[116:119], v[166:169], v[198:201], v[116:119]
	v_mfma_f32_16x16x32_bf16 v[116:119], v[170:173], v[202:205], v[116:119]
	v_mfma_f32_16x16x32_bf16 v[124:127], v[158:161], v[198:201], v[124:127]
	v_mfma_f32_16x16x32_bf16 v[124:127], v[162:165], v[202:205], v[124:127]
	v_mfma_f32_16x16x32_bf16 v[108:111], v[174:177], v[198:201], v[108:111]
	v_mfma_f32_16x16x32_bf16 v[108:111], v[178:181], v[202:205], v[108:111]
	v_mfma_f32_16x16x32_bf16 v[120:123], v[150:153], v[220:223], v[120:123]
	v_mfma_f32_16x16x32_bf16 v[120:123], v[154:157], v[224:227], v[120:123]
	v_mfma_f32_16x16x32_bf16 v[100:103], v[166:169], v[220:223], v[100:103]
	v_mfma_f32_16x16x32_bf16 v[100:103], v[170:173], v[224:227], v[100:103]
	v_mfma_f32_16x16x32_bf16 v[112:115], v[158:161], v[220:223], v[112:115]
	v_mfma_f32_16x16x32_bf16 v[112:115], v[162:165], v[224:227], v[112:115]
	v_mfma_f32_16x16x32_bf16 v[92:95], v[174:177], v[220:223], v[92:95]
	v_mfma_f32_16x16x32_bf16 v[92:95], v[178:181], v[224:227], v[92:95]
	s_setprio 0
	s_setprio 1
	v_mfma_f32_16x16x32_bf16 v[104:107], v[150:153], v[228:231], v[104:107]
	v_mfma_f32_16x16x32_bf16 v[104:107], v[154:157], v[232:235], v[104:107]
	v_mfma_f32_16x16x32_bf16 v[84:87], v[166:169], v[228:231], v[84:87]
	v_mfma_f32_16x16x32_bf16 v[84:87], v[170:173], v[232:235], v[84:87]
	v_mfma_f32_16x16x32_bf16 v[96:99], v[158:161], v[228:231], v[96:99]
	v_mfma_f32_16x16x32_bf16 v[96:99], v[162:165], v[232:235], v[96:99]
	v_mfma_f32_16x16x32_bf16 v[76:79], v[174:177], v[228:231], v[76:79]
	v_mfma_f32_16x16x32_bf16 v[76:79], v[178:181], v[232:235], v[76:79]
	v_mfma_f32_16x16x32_bf16 v[88:91], v[150:153], v[236:239], v[88:91]
	v_mfma_f32_16x16x32_bf16 v[88:91], v[154:157], v[240:243], v[88:91]
	v_mfma_f32_16x16x32_bf16 v[72:75], v[166:169], v[236:239], v[72:75]
	v_mfma_f32_16x16x32_bf16 v[72:75], v[170:173], v[240:243], v[72:75]
	v_mfma_f32_16x16x32_bf16 v[80:83], v[158:161], v[236:239], v[80:83]
	v_mfma_f32_16x16x32_bf16 v[80:83], v[162:165], v[240:243], v[80:83]
	v_mfma_f32_16x16x32_bf16 v[68:71], v[174:177], v[236:239], v[68:71]
	v_mfma_f32_16x16x32_bf16 v[68:71], v[178:181], v[240:243], v[68:71]
	s_setprio 0
	s_barrier
; #define PG8_STAGE(bufoff, gbase, voff) do { _Pragma("unroll") for (int _i = 0; _i < 2; ++_i) \
;         __builtin_amdgcn_global_load_lds((const unsigned*)((const char*)(gbase) + (voff)[_i]), (PG8_LAS unsigned*)(lds + (bufoff) + ldsw + _i * 8192), 16, 0, 0); } while (0)
; #define PG8_LDA(dst, b, h) do { _Pragma("unroll") for (int m = 0; m < 4; ++m) _Pragma("unroll") for (int k = 0; k < 2; ++k) dst[m][k] = *(const PG8_LAS bf16x8*)(lds + PG8_SA(b, h) + aoff + m * 2048 + k * 1024); } while (0)
; #define PG8_MMA(ai, bj, At, Bt) do { __builtin_amdgcn_s_setprio(1); _Pragma("unroll") for (int m = 0; m < 4; ++m) _Pragma("unroll") for (int n = 0; n < 2; ++n) _Pragma("unroll") for (int k = 0; k < 2; ++k) \
;         acc[ai][bj][m][n] = __builtin_amdgcn_mfma_f32_16x16x32_bf16(Bt[n][k], At[m][k], acc[ai][bj][m][n], 0, 0, 0); __builtin_amdgcn_s_setprio(0); } while (0)
; #define PG8_WAIT_V(n) asm volatile("s_waitcnt vmcnt(" #n ")" ::: "memory")
; #define PG8_WAIT_L(n) asm volatile("s_waitcnt lgkmcnt(" #n ")" ::: "memory")
; #define PG8_BAR __builtin_amdgcn_s_barrier()
; #define PG8_SCHED __builtin_amdgcn_sched_barrier(0)
; template <class Epi, class Sched, bool ALIGN_EPI = false, bool SP2 = false>
; __device__ __forceinline__ void gemm_phase(PG8_LAS unsigned char* lds, const Gemm g, const Sched& S, const Epi& E) {
;     ...
;         for (int t = 0; t < nt; t += 2) {
;     ...
;             PG8_LDA(At, 1, 1); PG8_STAGE(PG8_SB(1, 0), b3, voffB); PG8_STAGE(PG8_SB(1, 1), b3 + hstep, voffB); PG8_STAGE(PG8_SA(1, 0), a3, voffA);
;             PG8_WAIT_V(8); PG8_WAIT_L(0); PG8_BAR; PG8_MMA(1, 0, At, B0); PG8_MMA(1, 1, At, B1); PG8_BAR; PG8_SCHED;
	s_add_i32 s18, s44, s23
	v_lshl_add_u64 v[144:145], v[144:145], 0, s[34:35]
	s_mov_b32 m0, s18
	ds_read_b128 v[198:201], v148 offset:49152
	ds_read_b128 v[202:205], v148 offset:50176
	ds_read_b128 v[220:223], v148 offset:51200
	ds_read_b128 v[224:227], v148 offset:52224
	ds_read_b128 v[228:231], v148 offset:53248
	ds_read_b128 v[232:235], v148 offset:54272
	ds_read_b128 v[236:239], v148 offset:55296
	ds_read_b128 v[240:243], v148 offset:56320
	global_load_lds_dwordx4 v[144:145], off
	s_add_i32 m0, s18, 0x2000
	s_add_u32 s16, s16, 0x80080
	v_lshl_add_u64 v[144:145], v[184:185], 0, s[34:35]
	s_addc_u32 s17, s17, 0
	s_add_i32 s18, s45, s23
	global_load_lds_dwordx4 v[144:145], off
	v_lshl_add_u64 v[144:145], s[16:17], 0, v[2:3]
	s_mov_b32 m0, s18
	s_nop 0
	global_load_lds_dwordx4 v[144:145], off
	v_lshl_add_u64 v[144:145], s[16:17], 0, v[132:133]
	s_add_i32 m0, s18, 0x2000
	s_nop 0
	global_load_lds_dwordx4 v[144:145], off
	v_lshl_add_u64 v[144:145], v[186:187], 0, s[34:35]
	s_mov_b32 m0, s28
	s_nop 0
	global_load_lds_dwordx4 v[144:145], off
	v_lshl_add_u64 v[144:145], v[196:197], 0, s[34:35]
	s_mov_b32 m0, s29
	s_nop 0
	global_load_lds_dwordx4 v[144:145], off
	s_waitcnt vmcnt(8)
	s_waitcnt lgkmcnt(0)
	s_barrier
	s_setprio 1
	s_waitcnt lgkmcnt(0)
	v_mfma_f32_16x16x32_bf16 v[64:67], v[150:153], v[198:201], v[64:67]
	v_mfma_f32_16x16x32_bf16 v[64:67], v[154:157], v[202:205], v[64:67]
	v_mfma_f32_16x16x32_bf16 v[52:55], v[166:169], v[198:201], v[52:55]
	v_mfma_f32_16x16x32_bf16 v[52:55], v[170:173], v[202:205], v[52:55]
	v_mfma_f32_16x16x32_bf16 v[60:63], v[158:161], v[198:201], v[60:63]
	v_mfma_f32_16x16x32_bf16 v[60:63], v[162:165], v[202:205], v[60:63]
	v_mfma_f32_16x16x32_bf16 v[44:47], v[174:177], v[198:201], v[44:47]
	v_mfma_f32_16x16x32_bf16 v[44:47], v[178:181], v[202:205], v[44:47]
	v_mfma_f32_16x16x32_bf16 v[56:59], v[150:153], v[220:223], v[56:59]
	v_mfma_f32_16x16x32_bf16 v[56:59], v[154:157], v[224:227], v[56:59]
	v_mfma_f32_16x16x32_bf16 v[36:39], v[166:169], v[220:223], v[36:39]
	v_mfma_f32_16x16x32_bf16 v[36:39], v[170:173], v[224:227], v[36:39]
	v_mfma_f32_16x16x32_bf16 v[48:51], v[158:161], v[220:223], v[48:51]
	v_mfma_f32_16x16x32_bf16 v[48:51], v[162:165], v[224:227], v[48:51]
	v_mfma_f32_16x16x32_bf16 v[28:31], v[174:177], v[220:223], v[28:31]
	v_mfma_f32_16x16x32_bf16 v[28:31], v[178:181], v[224:227], v[28:31]
	s_setprio 0
	s_setprio 1
	v_mfma_f32_16x16x32_bf16 v[40:43], v[150:153], v[228:231], v[40:43]
	v_mfma_f32_16x16x32_bf16 v[40:43], v[154:157], v[232:235], v[40:43]
	v_mfma_f32_16x16x32_bf16 v[20:23], v[166:169], v[228:231], v[20:23]
	v_mfma_f32_16x16x32_bf16 v[20:23], v[170:173], v[232:235], v[20:23]
	v_mfma_f32_16x16x32_bf16 v[32:35], v[158:161], v[228:231], v[32:35]
	v_mfma_f32_16x16x32_bf16 v[32:35], v[162:165], v[232:235], v[32:35]
	v_mfma_f32_16x16x32_bf16 v[12:15], v[174:177], v[228:231], v[12:15]
	v_mfma_f32_16x16x32_bf16 v[12:15], v[178:181], v[232:235], v[12:15]
	v_mfma_f32_16x16x32_bf16 v[24:27], v[150:153], v[236:239], v[24:27]
	v_mfma_f32_16x16x32_bf16 v[24:27], v[154:157], v[240:243], v[24:27]
	v_mfma_f32_16x16x32_bf16 v[8:11], v[166:169], v[236:239], v[8:11]
	v_mfma_f32_16x16x32_bf16 v[8:11], v[170:173], v[240:243], v[8:11]
	v_mfma_f32_16x16x32_bf16 v[16:19], v[158:161], v[236:239], v[16:19]
	v_mfma_f32_16x16x32_bf16 v[16:19], v[162:165], v[240:243], v[16:19]
	v_mfma_f32_16x16x32_bf16 v[4:7], v[174:177], v[236:239], v[4:7]
	v_mfma_f32_16x16x32_bf16 v[4:7], v[178:181], v[240:243], v[4:7]
	s_setprio 0
	s_barrier
	s_add_i32 s43, s43, 2
	s_add_u32 s14, s14, 0x100
	s_addc_u32 s15, s15, 0
	s_add_u32 s41, s41, 0x100
	s_addc_u32 s42, s42, 0
	s_cmp_gt_u32 s43, 29
	s_cbranch_scc0 .LBB11_913
	s_and_b64 vcc, exec, s[4:5]
	s_cbranch_vccz .LBB11_916
	s_barrier

; #define PG8_STAGE(bufoff, gbase, voff) do { _Pragma("unroll") for (int _i = 0; _i < 2; ++_i) \
;         __builtin_amdgcn_global_load_lds((const unsigned*)((const char*)(gbase) + (voff)[_i]), (PG8_LAS unsigned*)(lds + (bufoff) + ldsw + _i * 8192), 16, 0, 0); } while (0)
; #define PG8_LDA(dst, b, h) do { _Pragma("unroll") for (int m = 0; m < 4; ++m) _Pragma("unroll") for (int k = 0; k < 2; ++k) dst[m][k] = *(const PG8_LAS bf16x8*)(lds + PG8_SA(b, h) + aoff + m * 2048 + k * 1024); } while (0)
; #define PG8_LDB(dst, b, h) do { _Pragma("unroll") for (int n = 0; n < 2; ++n) _Pragma("unroll") for (int k = 0; k < 2; ++k) dst[n][k] = *(const PG8_LAS bf16x8*)(lds + PG8_SB(b, h) + boff + n * 2048 + k * 1024); } while (0)
; #define PG8_MMA(ai, bj, At, Bt) do { __builtin_amdgcn_s_setprio(1); _Pragma("unroll") for (int m = 0; m < 4; ++m) _Pragma("unroll") for (int n = 0; n < 2; ++n) _Pragma("unroll") for (int k = 0; k < 2; ++k) \
;         acc[ai][bj][m][n] = __builtin_amdgcn_mfma_f32_16x16x32_bf16(Bt[n][k], At[m][k], acc[ai][bj][m][n], 0, 0, 0); __builtin_amdgcn_s_setprio(0); } while (0)
; #define PG8_WAIT_V(n) asm volatile("s_waitcnt vmcnt(" #n ")" ::: "memory")
; #define PG8_WAIT_L(n) asm volatile("s_waitcnt lgkmcnt(" #n ")" ::: "memory")
; template <class Epi, class Sched, bool ALIGN_EPI = false, bool SP2 = false>
; __device__ __forceinline__ void gemm_phase(PG8_LAS unsigned char* lds, const Gemm g, const Sched& S, const Epi& E) {
;     ...
;             const bool last = (t == nt - 2);
;             const char* a1 = cA + (size_t)(t + 1) * kstep;
;             const char* a2 = last ? nA : cA + (size_t)(t + 2) * kstep; const char* b2 = last ? nB : cB + (size_t)(t + 2) * kstep;
;             const char* a3 = a2 + kstep; const char* b3 = b2 + kstep;
;             if (last && has_next) S.a_ready(nxt);
;             if constexpr (SP2) {
;             PG8_LDB(B0, 0, 0); PG8_LDB(B1, 0, 1); PG8_SCHED; PG8_LDA(At, 0, 0); PG8_STAGE(PG8_SA(1, 1), a1 + hstep, voffA);
;             PG8_WAIT_V(8); PG8_WAIT_L(0); PG8_BAR; PG8_MMA(0, 0, At, B0); PG8_MMA(0, 1, At, B1); PG8_BAR; PG8_SCHED;
;             PG8_LDA(At, 0, 1); PG8_STAGE(PG8_SB(0, 0), b2, voffB); PG8_STAGE(PG8_SB(0, 1), b2 + hstep, voffB); PG8_STAGE(PG8_SA(0, 0), a2, voffA);
;             PG8_WAIT_V(8); PG8_WAIT_L(0); PG8_BAR; PG8_MMA(1, 0, At, B0); PG8_MMA(1, 1, At, B1); PG8_BAR; PG8_SCHED;
.LBB11_1071:
	s_add_u32 s16, s14, 0xfff80080
	s_addc_u32 s17, s15, -1
	s_add_i32 s46, 0, 0x10000
	s_cmp_eq_u32 s45, 28
	s_cselect_b32 s19, s9, s17
	s_cselect_b32 s18, s41, s16
	v_add_u32_e32 v2, s46, v168
	s_cselect_b32 s17, s7, s44
	s_cselect_b32 s16, s42, s43
	s_add_i32 s48, 0, 0x14000
	ds_read_b128 v[132:135], v2
	ds_read_b128 v[136:139], v2 offset:1024
	ds_read_b128 v[140:143], v2 offset:2048
	ds_read_b128 v[144:147], v2 offset:3072
	v_add_u32_e32 v2, s48, v168
	ds_read_b128 v[170:173], v2
	ds_read_b128 v[174:177], v2 offset:1024
	ds_read_b128 v[178:181], v2 offset:2048
	ds_read_b128 v[198:201], v2 offset:3072
	v_lshl_add_u64 v[166:167], s[14:15], 0, v[162:163]
	s_add_i32 m0, s25, 0xc000
	ds_read_b128 v[202:205], v169
	ds_read_b128 v[220:223], v169 offset:1024
	ds_read_b128 v[224:227], v169 offset:2048
	ds_read_b128 v[228:231], v169 offset:3072
	ds_read_b128 v[232:235], v169 offset:4096
	ds_read_b128 v[236:239], v169 offset:5120
	ds_read_b128 v[240:243], v169 offset:6144
	ds_read_b128 v[244:247], v169 offset:7168
	global_load_lds_dwordx4 v[166:167], off
	v_lshl_add_u64 v[166:167], s[14:15], 0, v[164:165]
	s_add_i32 m0, s25, 0xe000
	s_nop 0
	global_load_lds_dwordx4 v[166:167], off
	s_waitcnt vmcnt(8)
	s_waitcnt lgkmcnt(0)
	s_barrier
	s_setprio 1
	s_waitcnt lgkmcnt(0)
	v_mfma_f32_16x16x32_bf16 v[128:131], v[132:135], v[202:205], v[128:131]
	v_mfma_f32_16x16x32_bf16 v[128:131], v[136:139], v[220:223], v[128:131]
	v_mfma_f32_16x16x32_bf16 v[116:119], v[170:173], v[202:205], v[116:119]
	v_mfma_f32_16x16x32_bf16 v[116:119], v[174:177], v[220:223], v[116:119]
	v_mfma_f32_16x16x32_bf16 v[124:127], v[140:143], v[202:205], v[124:127]
	v_mfma_f32_16x16x32_bf16 v[124:127], v[144:147], v[220:223], v[124:127]
	v_mfma_f32_16x16x32_bf16 v[108:111], v[178:181], v[202:205], v[108:111]
	v_mfma_f32_16x16x32_bf16 v[108:111], v[198:201], v[220:223], v[108:111]
	v_mfma_f32_16x16x32_bf16 v[120:123], v[132:135], v[224:227], v[120:123]
	v_mfma_f32_16x16x32_bf16 v[120:123], v[136:139], v[228:231], v[120:123]
	v_mfma_f32_16x16x32_bf16 v[100:103], v[170:173], v[224:227], v[100:103]
	v_mfma_f32_16x16x32_bf16 v[100:103], v[174:177], v[228:231], v[100:103]
	v_mfma_f32_16x16x32_bf16 v[112:115], v[140:143], v[224:227], v[112:115]
	v_mfma_f32_16x16x32_bf16 v[112:115], v[144:147], v[228:231], v[112:115]
	v_mfma_f32_16x16x32_bf16 v[92:95], v[178:181], v[224:227], v[92:95]
	v_mfma_f32_16x16x32_bf16 v[92:95], v[198:201], v[228:231], v[92:95]
	s_setprio 0
	s_setprio 1
	v_mfma_f32_16x16x32_bf16 v[104:107], v[132:135], v[232:235], v[104:107]
	v_mfma_f32_16x16x32_bf16 v[104:107], v[136:139], v[236:239], v[104:107]
	v_mfma_f32_16x16x32_bf16 v[84:87], v[170:173], v[232:235], v[84:87]
	v_mfma_f32_16x16x32_bf16 v[84:87], v[174:177], v[236:239], v[84:87]
	v_mfma_f32_16x16x32_bf16 v[96:99], v[140:143], v[232:235], v[96:99]
	v_mfma_f32_16x16x32_bf16 v[96:99], v[144:147], v[236:239], v[96:99]
	v_mfma_f32_16x16x32_bf16 v[76:79], v[178:181], v[232:235], v[76:79]
	v_mfma_f32_16x16x32_bf16 v[76:79], v[198:201], v[236:239], v[76:79]
	v_mfma_f32_16x16x32_bf16 v[88:91], v[132:135], v[240:243], v[88:91]
	v_mfma_f32_16x16x32_bf16 v[88:91], v[136:139], v[244:247], v[88:91]
	v_mfma_f32_16x16x32_bf16 v[72:75], v[170:173], v[240:243], v[72:75]
	v_mfma_f32_16x16x32_bf16 v[72:75], v[174:177], v[244:247], v[72:75]
	v_mfma_f32_16x16x32_bf16 v[80:83], v[140:143], v[240:243], v[80:83]
	v_mfma_f32_16x16x32_bf16 v[80:83], v[144:147], v[244:247], v[80:83]
	v_mfma_f32_16x16x32_bf16 v[68:71], v[178:181], v[240:243], v[68:71]
	v_mfma_f32_16x16x32_bf16 v[68:71], v[198:201], v[244:247], v[68:71]
	s_setprio 0
	s_barrier
	s_add_i32 s46, s46, s24
	v_lshl_add_u64 v[166:167], s[16:17], 0, v[154:155]
	s_mov_b32 m0, s46
	ds_read_b128 v[202:205], v169 offset:16384
	ds_read_b128 v[220:223], v169 offset:17408
	ds_read_b128 v[224:227], v169 offset:18432
	ds_read_b128 v[228:231], v169 offset:19456
	ds_read_b128 v[232:235], v169 offset:20480
	ds_read_b128 v[236:239], v169 offset:21504
	ds_read_b128 v[240:243], v169 offset:22528
	ds_read_b128 v[244:247], v169 offset:23552
	global_load_lds_dwordx4 v[166:167], off
	s_add_i32 m0, s46, 0x2000
	s_add_u32 s46, s16, 0x80000
	v_lshl_add_u64 v[196:197], s[16:17], 0, v[150:151]
	s_addc_u32 s47, s17, 0
	s_add_i32 s48, s48, s24
	global_load_lds_dwordx4 v[196:197], off
	v_lshl_add_u64 v[206:207], s[46:47], 0, v[154:155]
	s_mov_b32 m0, s48
	v_lshl_add_u64 v[184:185], s[18:19], 0, v[152:153]
	global_load_lds_dwordx4 v[206:207], off
	v_lshl_add_u64 v[206:207], s[46:47], 0, v[150:151]
	s_add_i32 m0, s48, 0x2000
	s_nop 0
	global_load_lds_dwordx4 v[206:207], off
	v_lshl_add_u64 v[206:207], s[18:19], 0, v[156:157]
	s_mov_b32 m0, s25
	s_nop 0
	global_load_lds_dwordx4 v[206:207], off
	s_mov_b32 m0, s26
	s_nop 0
	global_load_lds_dwordx4 v[184:185], off
	s_waitcnt vmcnt(8)
	s_waitcnt lgkmcnt(0)
	s_barrier
; #define PG8_STAGE(bufoff, gbase, voff) do { _Pragma("unroll") for (int _i = 0; _i < 2; ++_i) \
;         __builtin_amdgcn_global_load_lds((const unsigned*)((const char*)(gbase) + (voff)[_i]), (PG8_LAS unsigned*)(lds + (bufoff) + ldsw + _i * 8192), 16, 0, 0); } while (0)
; #define PG8_LDA(dst, b, h) do { _Pragma("unroll") for (int m = 0; m < 4; ++m) _Pragma("unroll") for (int k = 0; k < 2; ++k) dst[m][k] = *(const PG8_LAS bf16x8*)(lds + PG8_SA(b, h) + aoff + m * 2048 + k * 1024); } while (0)
; #define PG8_LDB(dst, b, h) do { _Pragma("unroll") for (int n = 0; n < 2; ++n) _Pragma("unroll") for (int k = 0; k < 2; ++k) dst[n][k] = *(const PG8_LAS bf16x8*)(lds + PG8_SB(b, h) + boff + n * 2048 + k * 1024); } while (0)
; #define PG8_MMA(ai, bj, At, Bt) do { __builtin_amdgcn_s_setprio(1); _Pragma("unroll") for (int m = 0; m < 4; ++m) _Pragma("unroll") for (int n = 0; n < 2; ++n) _Pragma("unroll") for (int k = 0; k < 2; ++k) \
;         acc[ai][bj][m][n] = __builtin_amdgcn_mfma_f32_16x16x32_bf16(Bt[n][k], At[m][k], acc[ai][bj][m][n], 0, 0, 0); __builtin_amdgcn_s_setprio(0); } while (0)
; #define PG8_WAIT_V(n) asm volatile("s_waitcnt vmcnt(" #n ")" ::: "memory")
; #define PG8_WAIT_L(n) asm volatile("s_waitcnt lgkmcnt(" #n ")" ::: "memory")
; #define PG8_BAR __builtin_amdgcn_s_barrier()
; #define PG8_SCHED __builtin_amdgcn_sched_barrier(0)
; template <class Epi, class Sched, bool ALIGN_EPI = false, bool SP2 = false>
; __device__ __forceinline__ void gemm_phase(PG8_LAS unsigned char* lds, const Gemm g, const Sched& S, const Epi& E) {
;     ...
;             PG8_WAIT_V(8); PG8_WAIT_L(0); PG8_BAR; PG8_MMA(1, 0, At, B0); PG8_MMA(1, 1, At, B1); PG8_BAR; PG8_SCHED;
;             PG8_LDB(B0, 1, 0); PG8_LDB(B1, 1, 1); PG8_SCHED; PG8_LDA(At, 1, 0); PG8_STAGE(PG8_SA(0, 1), a2 + hstep, voffA);
;             PG8_WAIT_V(8); PG8_WAIT_L(0); PG8_BAR; PG8_MMA(0, 0, At, B0); PG8_MMA(0, 1, At, B1); PG8_BAR; PG8_SCHED;
	s_setprio 1
	s_waitcnt lgkmcnt(0)
	v_mfma_f32_16x16x32_bf16 v[64:67], v[132:135], v[202:205], v[64:67]
	v_mfma_f32_16x16x32_bf16 v[64:67], v[136:139], v[220:223], v[64:67]
	v_mfma_f32_16x16x32_bf16 v[52:55], v[170:173], v[202:205], v[52:55]
	v_mfma_f32_16x16x32_bf16 v[52:55], v[174:177], v[220:223], v[52:55]
	v_mfma_f32_16x16x32_bf16 v[60:63], v[140:143], v[202:205], v[60:63]
	v_mfma_f32_16x16x32_bf16 v[60:63], v[144:147], v[220:223], v[60:63]
	v_mfma_f32_16x16x32_bf16 v[44:47], v[178:181], v[202:205], v[44:47]
	v_mfma_f32_16x16x32_bf16 v[44:47], v[198:201], v[220:223], v[44:47]
	v_mfma_f32_16x16x32_bf16 v[56:59], v[132:135], v[224:227], v[56:59]
	v_mfma_f32_16x16x32_bf16 v[56:59], v[136:139], v[228:231], v[56:59]
	v_mfma_f32_16x16x32_bf16 v[36:39], v[170:173], v[224:227], v[36:39]
	v_mfma_f32_16x16x32_bf16 v[36:39], v[174:177], v[228:231], v[36:39]
	v_mfma_f32_16x16x32_bf16 v[48:51], v[140:143], v[224:227], v[48:51]
	v_mfma_f32_16x16x32_bf16 v[48:51], v[144:147], v[228:231], v[48:51]
	v_mfma_f32_16x16x32_bf16 v[28:31], v[178:181], v[224:227], v[28:31]
	v_mfma_f32_16x16x32_bf16 v[28:31], v[198:201], v[228:231], v[28:31]
	s_setprio 0
	s_setprio 1
	v_mfma_f32_16x16x32_bf16 v[40:43], v[132:135], v[232:235], v[40:43]
	v_mfma_f32_16x16x32_bf16 v[40:43], v[136:139], v[236:239], v[40:43]
	v_mfma_f32_16x16x32_bf16 v[20:23], v[170:173], v[232:235], v[20:23]
	v_mfma_f32_16x16x32_bf16 v[20:23], v[174:177], v[236:239], v[20:23]
	v_mfma_f32_16x16x32_bf16 v[32:35], v[140:143], v[232:235], v[32:35]
	v_mfma_f32_16x16x32_bf16 v[32:35], v[144:147], v[236:239], v[32:35]
	v_mfma_f32_16x16x32_bf16 v[12:15], v[178:181], v[232:235], v[12:15]
	v_mfma_f32_16x16x32_bf16 v[12:15], v[198:201], v[236:239], v[12:15]
	v_mfma_f32_16x16x32_bf16 v[24:27], v[132:135], v[240:243], v[24:27]
	v_mfma_f32_16x16x32_bf16 v[24:27], v[136:139], v[244:247], v[24:27]
	v_mfma_f32_16x16x32_bf16 v[8:11], v[170:173], v[240:243], v[8:11]
	v_mfma_f32_16x16x32_bf16 v[8:11], v[174:177], v[244:247], v[8:11]
	v_mfma_f32_16x16x32_bf16 v[16:19], v[140:143], v[240:243], v[16:19]
	v_mfma_f32_16x16x32_bf16 v[16:19], v[144:147], v[244:247], v[16:19]
	v_mfma_f32_16x16x32_bf16 v[4:7], v[178:181], v[240:243], v[4:7]
	v_mfma_f32_16x16x32_bf16 v[4:7], v[198:201], v[244:247], v[4:7]
	s_setprio 0
	s_barrier
	s_add_i32 s46, 0, 0x18000
	v_add_u32_e32 v2, s46, v168
	s_add_i32 s47, 0, 0x1c000
	ds_read_b128 v[132:135], v2
	ds_read_b128 v[136:139], v2 offset:1024
	ds_read_b128 v[140:143], v2 offset:2048
	ds_read_b128 v[144:147], v2 offset:3072
	v_add_u32_e32 v2, s47, v168
	ds_read_b128 v[170:173], v2
	ds_read_b128 v[174:177], v2 offset:1024
	ds_read_b128 v[178:181], v2 offset:2048
	ds_read_b128 v[198:201], v2 offset:3072
	s_add_u32 s18, s18, 0x80000
	s_addc_u32 s19, s19, 0
	s_mov_b32 m0, s27
	v_lshl_add_u64 v[186:187], s[18:19], 0, v[156:157]
	ds_read_b128 v[202:205], v169 offset:32768
	ds_read_b128 v[220:223], v169 offset:33792
	ds_read_b128 v[224:227], v169 offset:34816
	ds_read_b128 v[228:231], v169 offset:35840
	ds_read_b128 v[232:235], v169 offset:36864
	ds_read_b128 v[236:239], v169 offset:37888
	ds_read_b128 v[240:243], v169 offset:38912
	ds_read_b128 v[244:247], v169 offset:39936
	global_load_lds_dwordx4 v[186:187], off
	v_lshl_add_u64 v[186:187], s[18:19], 0, v[152:153]
	s_mov_b32 m0, s28
	s_nop 0
	global_load_lds_dwordx4 v[186:187], off
	s_waitcnt vmcnt(8)
	s_waitcnt lgkmcnt(0)
	s_barrier
	s_setprio 1
	s_waitcnt lgkmcnt(0)
	v_mfma_f32_16x16x32_bf16 v[128:131], v[132:135], v[202:205], v[128:131]
	v_mfma_f32_16x16x32_bf16 v[128:131], v[136:139], v[220:223], v[128:131]
	v_mfma_f32_16x16x32_bf16 v[116:119], v[170:173], v[202:205], v[116:119]
	v_mfma_f32_16x16x32_bf16 v[116:119], v[174:177], v[220:223], v[116:119]
	v_mfma_f32_16x16x32_bf16 v[124:127], v[140:143], v[202:205], v[124:127]
	v_mfma_f32_16x16x32_bf16 v[124:127], v[144:147], v[220:223], v[124:127]
	v_mfma_f32_16x16x32_bf16 v[108:111], v[178:181], v[202:205], v[108:111]
	v_mfma_f32_16x16x32_bf16 v[108:111], v[198:201], v[220:223], v[108:111]
	v_mfma_f32_16x16x32_bf16 v[120:123], v[132:135], v[224:227], v[120:123]
	v_mfma_f32_16x16x32_bf16 v[120:123], v[136:139], v[228:231], v[120:123]
	v_mfma_f32_16x16x32_bf16 v[100:103], v[170:173], v[224:227], v[100:103]
	v_mfma_f32_16x16x32_bf16 v[100:103], v[174:177], v[228:231], v[100:103]
	v_mfma_f32_16x16x32_bf16 v[112:115], v[140:143], v[224:227], v[112:115]
	v_mfma_f32_16x16x32_bf16 v[112:115], v[144:147], v[228:231], v[112:115]
	v_mfma_f32_16x16x32_bf16 v[92:95], v[178:181], v[224:227], v[92:95]
	v_mfma_f32_16x16x32_bf16 v[92:95], v[198:201], v[228:231], v[92:95]
	s_setprio 0
	s_setprio 1
	v_mfma_f32_16x16x32_bf16 v[104:107], v[132:135], v[232:235], v[104:107]
	v_mfma_f32_16x16x32_bf16 v[104:107], v[136:139], v[236:239], v[104:107]
	v_mfma_f32_16x16x32_bf16 v[84:87], v[170:173], v[232:235], v[84:87]
	v_mfma_f32_16x16x32_bf16 v[84:87], v[174:177], v[236:239], v[84:87]
	v_mfma_f32_16x16x32_bf16 v[96:99], v[140:143], v[232:235], v[96:99]
	v_mfma_f32_16x16x32_bf16 v[96:99], v[144:147], v[236:239], v[96:99]
	v_mfma_f32_16x16x32_bf16 v[76:79], v[178:181], v[232:235], v[76:79]
	v_mfma_f32_16x16x32_bf16 v[76:79], v[198:201], v[236:239], v[76:79]
	v_mfma_f32_16x16x32_bf16 v[88:91], v[132:135], v[240:243], v[88:91]
	v_mfma_f32_16x16x32_bf16 v[88:91], v[136:139], v[244:247], v[88:91]
	v_mfma_f32_16x16x32_bf16 v[72:75], v[170:173], v[240:243], v[72:75]
	v_mfma_f32_16x16x32_bf16 v[72:75], v[174:177], v[244:247], v[72:75]
	v_mfma_f32_16x16x32_bf16 v[80:83], v[140:143], v[240:243], v[80:83]
	v_mfma_f32_16x16x32_bf16 v[80:83], v[144:147], v[244:247], v[80:83]
	v_mfma_f32_16x16x32_bf16 v[68:71], v[178:181], v[240:243], v[68:71]
	v_mfma_f32_16x16x32_bf16 v[68:71], v[198:201], v[244:247], v[68:71]
	s_setprio 0
	s_barrier
; #define PG8_STAGE(bufoff, gbase, voff) do { _Pragma("unroll") for (int _i = 0; _i < 2; ++_i) \
;         __builtin_amdgcn_global_load_lds((const unsigned*)((const char*)(gbase) + (voff)[_i]), (PG8_LAS unsigned*)(lds + (bufoff) + ldsw + _i * 8192), 16, 0, 0); } while (0)
; #define PG8_LDA(dst, b, h) do { _Pragma("unroll") for (int m = 0; m < 4; ++m) _Pragma("unroll") for (int k = 0; k < 2; ++k) dst[m][k] = *(const PG8_LAS bf16x8*)(lds + PG8_SA(b, h) + aoff + m * 2048 + k * 1024); } while (0)
; #define PG8_MMA(ai, bj, At, Bt) do { __builtin_amdgcn_s_setprio(1); _Pragma("unroll") for (int m = 0; m < 4; ++m) _Pragma("unroll") for (int n = 0; n < 2; ++n) _Pragma("unroll") for (int k = 0; k < 2; ++k) \
;         acc[ai][bj][m][n] = __builtin_amdgcn_mfma_f32_16x16x32_bf16(Bt[n][k], At[m][k], acc[ai][bj][m][n], 0, 0, 0); __builtin_amdgcn_s_setprio(0); } while (0)
; #define PG8_WAIT_V(n) asm volatile("s_waitcnt vmcnt(" #n ")" ::: "memory")
; #define PG8_WAIT_L(n) asm volatile("s_waitcnt lgkmcnt(" #n ")" ::: "memory")
; #define PG8_BAR __builtin_amdgcn_s_barrier()
; #define PG8_SCHED __builtin_amdgcn_sched_barrier(0)
; template <class Epi, class Sched, bool ALIGN_EPI = false, bool SP2 = false>
; __device__ __forceinline__ void gemm_phase(PG8_LAS unsigned char* lds, const Gemm g, const Sched& S, const Epi& E) {
;     ...
;         for (int t = 0; t < nt; t += 2) {
;     ...
;             PG8_LDA(At, 1, 1); PG8_STAGE(PG8_SB(1, 0), b3, voffB); PG8_STAGE(PG8_SB(1, 1), b3 + hstep, voffB); PG8_STAGE(PG8_SA(1, 0), a3, voffA);
;             PG8_WAIT_V(8); PG8_WAIT_L(0); PG8_BAR; PG8_MMA(1, 0, At, B0); PG8_MMA(1, 1, At, B1); PG8_BAR; PG8_SCHED;
	s_add_i32 s18, s46, s24
	v_lshl_add_u64 v[166:167], v[166:167], 0, s[34:35]
	s_mov_b32 m0, s18
	ds_read_b128 v[202:205], v169 offset:49152
	ds_read_b128 v[220:223], v169 offset:50176
	ds_read_b128 v[224:227], v169 offset:51200
	ds_read_b128 v[228:231], v169 offset:52224
	ds_read_b128 v[232:235], v169 offset:53248
	ds_read_b128 v[236:239], v169 offset:54272
	ds_read_b128 v[240:243], v169 offset:55296
	ds_read_b128 v[244:247], v169 offset:56320
	global_load_lds_dwordx4 v[166:167], off
	s_add_i32 m0, s18, 0x2000
	s_add_u32 s16, s16, 0x80080
	v_lshl_add_u64 v[166:167], v[196:197], 0, s[34:35]
	s_addc_u32 s17, s17, 0
	s_add_i32 s18, s47, s24
	global_load_lds_dwordx4 v[166:167], off
	v_lshl_add_u64 v[166:167], s[16:17], 0, v[154:155]
	s_mov_b32 m0, s18
	s_nop 0
	global_load_lds_dwordx4 v[166:167], off
	v_lshl_add_u64 v[166:167], s[16:17], 0, v[150:151]
	s_add_i32 m0, s18, 0x2000
	s_nop 0
	global_load_lds_dwordx4 v[166:167], off
	v_lshl_add_u64 v[166:167], v[206:207], 0, s[34:35]
	s_mov_b32 m0, s33
	s_nop 0
	global_load_lds_dwordx4 v[166:167], off
	v_lshl_add_u64 v[166:167], v[184:185], 0, s[34:35]
	s_mov_b32 m0, s38
	s_nop 0
	global_load_lds_dwordx4 v[166:167], off
	s_waitcnt vmcnt(8)
	s_waitcnt lgkmcnt(0)
	s_barrier
	s_setprio 1
	s_waitcnt lgkmcnt(0)
	v_mfma_f32_16x16x32_bf16 v[64:67], v[132:135], v[202:205], v[64:67]
	v_mfma_f32_16x16x32_bf16 v[64:67], v[136:139], v[220:223], v[64:67]
	v_mfma_f32_16x16x32_bf16 v[52:55], v[170:173], v[202:205], v[52:55]
	v_mfma_f32_16x16x32_bf16 v[52:55], v[174:177], v[220:223], v[52:55]
	v_mfma_f32_16x16x32_bf16 v[60:63], v[140:143], v[202:205], v[60:63]
	v_mfma_f32_16x16x32_bf16 v[60:63], v[144:147], v[220:223], v[60:63]
	v_mfma_f32_16x16x32_bf16 v[44:47], v[178:181], v[202:205], v[44:47]
	v_mfma_f32_16x16x32_bf16 v[44:47], v[198:201], v[220:223], v[44:47]
	v_mfma_f32_16x16x32_bf16 v[56:59], v[132:135], v[224:227], v[56:59]
	v_mfma_f32_16x16x32_bf16 v[56:59], v[136:139], v[228:231], v[56:59]
	v_mfma_f32_16x16x32_bf16 v[36:39], v[170:173], v[224:227], v[36:39]
	v_mfma_f32_16x16x32_bf16 v[36:39], v[174:177], v[228:231], v[36:39]
	v_mfma_f32_16x16x32_bf16 v[48:51], v[140:143], v[224:227], v[48:51]
	v_mfma_f32_16x16x32_bf16 v[48:51], v[144:147], v[228:231], v[48:51]
	v_mfma_f32_16x16x32_bf16 v[28:31], v[178:181], v[224:227], v[28:31]
	v_mfma_f32_16x16x32_bf16 v[28:31], v[198:201], v[228:231], v[28:31]
	s_setprio 0
	s_setprio 1
	v_mfma_f32_16x16x32_bf16 v[40:43], v[132:135], v[232:235], v[40:43]
	v_mfma_f32_16x16x32_bf16 v[40:43], v[136:139], v[236:239], v[40:43]
	v_mfma_f32_16x16x32_bf16 v[20:23], v[170:173], v[232:235], v[20:23]
	v_mfma_f32_16x16x32_bf16 v[20:23], v[174:177], v[236:239], v[20:23]
	v_mfma_f32_16x16x32_bf16 v[32:35], v[140:143], v[232:235], v[32:35]
	v_mfma_f32_16x16x32_bf16 v[32:35], v[144:147], v[236:239], v[32:35]
	v_mfma_f32_16x16x32_bf16 v[12:15], v[178:181], v[232:235], v[12:15]
	v_mfma_f32_16x16x32_bf16 v[12:15], v[198:201], v[236:239], v[12:15]
	v_mfma_f32_16x16x32_bf16 v[24:27], v[132:135], v[240:243], v[24:27]
	v_mfma_f32_16x16x32_bf16 v[24:27], v[136:139], v[244:247], v[24:27]
	v_mfma_f32_16x16x32_bf16 v[8:11], v[170:173], v[240:243], v[8:11]
	v_mfma_f32_16x16x32_bf16 v[8:11], v[174:177], v[244:247], v[8:11]
	v_mfma_f32_16x16x32_bf16 v[16:19], v[140:143], v[240:243], v[16:19]
	v_mfma_f32_16x16x32_bf16 v[16:19], v[144:147], v[244:247], v[16:19]
	v_mfma_f32_16x16x32_bf16 v[4:7], v[178:181], v[240:243], v[4:7]
	v_mfma_f32_16x16x32_bf16 v[4:7], v[198:201], v[244:247], v[4:7]
	s_setprio 0
	s_barrier
	s_add_i32 s45, s45, 2
	s_add_u32 s14, s14, 0x100
	s_addc_u32 s15, s15, 0
	s_add_u32 s43, s43, 0x100
	s_addc_u32 s44, s44, 0
	s_cmp_gt_u32 s45, 29
	s_cbranch_scc0 .LBB11_1071
	s_and_b64 vcc, exec, s[4:5]
	s_cbranch_vccz .LBB11_1074
	s_barrier

; #define PG8_STAGE(bufoff, gbase, voff) do { _Pragma("unroll") for (int _i = 0; _i < 2; ++_i) \
;         __builtin_amdgcn_global_load_lds((const unsigned*)((const char*)(gbase) + (voff)[_i]), (PG8_LAS unsigned*)(lds + (bufoff) + ldsw + _i * 8192), 16, 0, 0); } while (0)
; #define PG8_LDA(dst, b, h) do { _Pragma("unroll") for (int m = 0; m < 4; ++m) _Pragma("unroll") for (int k = 0; k < 2; ++k) dst[m][k] = *(const PG8_LAS bf16x8*)(lds + PG8_SA(b, h) + aoff + m * 2048 + k * 1024); } while (0)
; #define PG8_LDB(dst, b, h) do { _Pragma("unroll") for (int n = 0; n < 2; ++n) _Pragma("unroll") for (int k = 0; k < 2; ++k) dst[n][k] = *(const PG8_LAS bf16x8*)(lds + PG8_SB(b, h) + boff + n * 2048 + k * 1024); } while (0)
; #define PG8_MMA(ai, bj, At, Bt) do { __builtin_amdgcn_s_setprio(1); _Pragma("unroll") for (int m = 0; m < 4; ++m) _Pragma("unroll") for (int n = 0; n < 2; ++n) _Pragma("unroll") for (int k = 0; k < 2; ++k) \
;         acc[ai][bj][m][n] = __builtin_amdgcn_mfma_f32_16x16x32_bf16(Bt[n][k], At[m][k], acc[ai][bj][m][n], 0, 0, 0); __builtin_amdgcn_s_setprio(0); } while (0)
; #define PG8_WAIT_V(n) asm volatile("s_waitcnt vmcnt(" #n ")" ::: "memory")
; #define PG8_WAIT_L(n) asm volatile("s_waitcnt lgkmcnt(" #n ")" ::: "memory")
; template <class Epi, class Sched, bool ALIGN_EPI = false, bool SP2 = false>
; __device__ __forceinline__ void gemm_phase(PG8_LAS unsigned char* lds, const Gemm g, const Sched& S, const Epi& E) {
;     ...
;             const bool last = (t == nt - 2);
;             const char* a1 = cA + (size_t)(t + 1) * kstep;
;             const char* a2 = last ? nA : cA + (size_t)(t + 2) * kstep; const char* b2 = last ? nB : cB + (size_t)(t + 2) * kstep;
;             const char* a3 = a2 + kstep; const char* b3 = b2 + kstep;
;             if (last && has_next) S.a_ready(nxt);
;             if constexpr (SP2) {
;             PG8_LDB(B0, 0, 0); PG8_LDB(B1, 0, 1); PG8_SCHED; PG8_LDA(At, 0, 0); PG8_STAGE(PG8_SA(1, 1), a1 + hstep, voffA);
;             PG8_WAIT_V(8); PG8_WAIT_L(0); PG8_BAR; PG8_MMA(0, 0, At, B0); PG8_MMA(0, 1, At, B1); PG8_BAR; PG8_SCHED;
;             PG8_LDA(At, 0, 1); PG8_STAGE(PG8_SB(0, 0), b2, voffB); PG8_STAGE(PG8_SB(0, 1), b2 + hstep, voffB); PG8_STAGE(PG8_SA(0, 0), a2, voffA);
;             PG8_WAIT_V(8); PG8_WAIT_L(0); PG8_BAR; PG8_MMA(1, 0, At, B0); PG8_MMA(1, 1, At, B1); PG8_BAR; PG8_SCHED;
.LBB11_1896:
	s_add_i32 s56, s22, 2
	s_add_u32 s57, s16, s20
	s_addc_u32 s23, s17, s21
	s_add_u32 s58, s14, s20
	s_addc_u32 s59, s15, s21
	s_add_i32 s60, 0, 0x10000
	s_cmp_eq_u32 s49, s22
	s_cselect_b32 s23, s5, s23
	s_cselect_b32 s22, s4, s57
	s_cselect_b32 s59, s19, s59
	s_cselect_b32 s58, s18, s58
	s_add_i32 s57, 0, 0x14000
	v_add_u32_e32 v156, s60, v1
	v_add_u32_e32 v174, s57, v1
	ds_read_b128 v[144:147], v156
	ds_read_b128 v[148:151], v156 offset:1024
	ds_read_b128 v[152:155], v156 offset:2048
	ds_read_b128 v[156:159], v156 offset:3072
	ds_read_b128 v[160:163], v174
	ds_read_b128 v[166:169], v174 offset:1024
	ds_read_b128 v[170:173], v174 offset:2048
	ds_read_b128 v[174:177], v174 offset:3072
	v_lshl_add_u64 v[184:185], s[16:17], 0, v[140:141]
	s_add_i32 m0, s45, 0xc000
	ds_read_b128 v[178:181], v143
	ds_read_b128 v[198:201], v143 offset:1024
	ds_read_b128 v[202:205], v143 offset:2048
	ds_read_b128 v[220:223], v143 offset:3072
	ds_read_b128 v[224:227], v143 offset:4096
	ds_read_b128 v[228:231], v143 offset:5120
	ds_read_b128 v[232:235], v143 offset:6144
	ds_read_b128 v[236:239], v143 offset:7168
	global_load_lds_dwordx4 v[184:185], off
	v_lshl_add_u64 v[184:185], s[16:17], 0, v[138:139]
	s_add_i32 m0, s45, 0xe000
	s_nop 0
	global_load_lds_dwordx4 v[184:185], off
	s_waitcnt vmcnt(8)
	s_waitcnt lgkmcnt(0)
	s_barrier
	s_setprio 1
	s_waitcnt lgkmcnt(0)
	v_mfma_f32_16x16x32_bf16 v[100:103], v[144:147], v[178:181], v[100:103]
	v_mfma_f32_16x16x32_bf16 v[100:103], v[148:151], v[198:201], v[100:103]
	v_mfma_f32_16x16x32_bf16 v[16:19], v[160:163], v[178:181], v[16:19]
	v_mfma_f32_16x16x32_bf16 v[16:19], v[166:169], v[198:201], v[16:19]
	v_mfma_f32_16x16x32_bf16 v[68:71], v[152:155], v[178:181], v[68:71]
	v_mfma_f32_16x16x32_bf16 v[68:71], v[156:159], v[198:201], v[68:71]
	v_mfma_f32_16x16x32_bf16 v[4:7], v[170:173], v[178:181], v[4:7]
	v_mfma_f32_16x16x32_bf16 v[4:7], v[174:177], v[198:201], v[4:7]
	v_mfma_f32_16x16x32_bf16 v[116:119], v[144:147], v[202:205], v[116:119]
	v_mfma_f32_16x16x32_bf16 v[116:119], v[148:151], v[220:223], v[116:119]
	v_mfma_f32_16x16x32_bf16 v[32:35], v[160:163], v[202:205], v[32:35]
	v_mfma_f32_16x16x32_bf16 v[32:35], v[166:169], v[220:223], v[32:35]
	v_mfma_f32_16x16x32_bf16 v[80:83], v[152:155], v[202:205], v[80:83]
	v_mfma_f32_16x16x32_bf16 v[80:83], v[156:159], v[220:223], v[80:83]
	v_mfma_f32_16x16x32_bf16 v[8:11], v[170:173], v[202:205], v[8:11]
	v_mfma_f32_16x16x32_bf16 v[8:11], v[174:177], v[220:223], v[8:11]
	s_setprio 0
	s_setprio 1
	v_mfma_f32_16x16x32_bf16 v[124:127], v[144:147], v[224:227], v[124:127]
	v_mfma_f32_16x16x32_bf16 v[124:127], v[148:151], v[228:231], v[124:127]
	v_mfma_f32_16x16x32_bf16 v[48:51], v[160:163], v[224:227], v[48:51]
	v_mfma_f32_16x16x32_bf16 v[48:51], v[166:169], v[228:231], v[48:51]
	v_mfma_f32_16x16x32_bf16 v[104:107], v[152:155], v[224:227], v[104:107]
	v_mfma_f32_16x16x32_bf16 v[104:107], v[156:159], v[228:231], v[104:107]
	v_mfma_f32_16x16x32_bf16 v[12:15], v[170:173], v[224:227], v[12:15]
	v_mfma_f32_16x16x32_bf16 v[12:15], v[174:177], v[228:231], v[12:15]
	v_mfma_f32_16x16x32_bf16 v[128:131], v[144:147], v[232:235], v[128:131]
	v_mfma_f32_16x16x32_bf16 v[128:131], v[148:151], v[236:239], v[128:131]
	v_mfma_f32_16x16x32_bf16 v[76:79], v[160:163], v[232:235], v[76:79]
	v_mfma_f32_16x16x32_bf16 v[76:79], v[166:169], v[236:239], v[76:79]
	v_mfma_f32_16x16x32_bf16 v[120:123], v[152:155], v[232:235], v[120:123]
	v_mfma_f32_16x16x32_bf16 v[120:123], v[156:159], v[236:239], v[120:123]
	v_mfma_f32_16x16x32_bf16 v[24:27], v[170:173], v[232:235], v[24:27]
	v_mfma_f32_16x16x32_bf16 v[24:27], v[174:177], v[236:239], v[24:27]
	s_setprio 0
	s_barrier
	s_add_i32 s60, s60, s13
	v_lshl_add_u64 v[184:185], s[58:59], 0, v[2:3]
	s_mov_b32 m0, s60
	ds_read_b128 v[178:181], v143 offset:16384
	ds_read_b128 v[198:201], v143 offset:17408
	ds_read_b128 v[202:205], v143 offset:18432
	ds_read_b128 v[220:223], v143 offset:19456
	ds_read_b128 v[224:227], v143 offset:20480
	ds_read_b128 v[228:231], v143 offset:21504
	ds_read_b128 v[232:235], v143 offset:22528
	ds_read_b128 v[236:239], v143 offset:23552
	global_load_lds_dwordx4 v[184:185], off
	s_add_i32 m0, s60, 0x2000
	v_lshl_add_u64 v[186:187], s[58:59], 0, v[132:133]
	s_add_u32 s58, s58, s33
	s_addc_u32 s59, s59, 0
	s_add_i32 s57, s57, s13
	global_load_lds_dwordx4 v[186:187], off
	v_lshl_add_u64 v[196:197], s[58:59], 0, v[2:3]
	s_mov_b32 m0, s57
	v_lshl_add_u64 v[206:207], s[58:59], 0, v[132:133]
	global_load_lds_dwordx4 v[196:197], off
	s_add_i32 m0, s57, 0x2000
	v_lshl_add_u64 v[240:241], s[22:23], 0, v[2:3]
	global_load_lds_dwordx4 v[206:207], off
	s_mov_b32 m0, s45
	v_lshl_add_u64 v[242:243], s[22:23], 0, v[132:133]
	global_load_lds_dwordx4 v[240:241], off
	s_mov_b32 m0, s46
	s_nop 0
	global_load_lds_dwordx4 v[242:243], off
	s_waitcnt vmcnt(8)
	s_waitcnt lgkmcnt(0)
	s_barrier
; #define PG8_STAGE(bufoff, gbase, voff) do { _Pragma("unroll") for (int _i = 0; _i < 2; ++_i) \
;         __builtin_amdgcn_global_load_lds((const unsigned*)((const char*)(gbase) + (voff)[_i]), (PG8_LAS unsigned*)(lds + (bufoff) + ldsw + _i * 8192), 16, 0, 0); } while (0)
; #define PG8_LDA(dst, b, h) do { _Pragma("unroll") for (int m = 0; m < 4; ++m) _Pragma("unroll") for (int k = 0; k < 2; ++k) dst[m][k] = *(const PG8_LAS bf16x8*)(lds + PG8_SA(b, h) + aoff + m * 2048 + k * 1024); } while (0)
; #define PG8_LDB(dst, b, h) do { _Pragma("unroll") for (int n = 0; n < 2; ++n) _Pragma("unroll") for (int k = 0; k < 2; ++k) dst[n][k] = *(const PG8_LAS bf16x8*)(lds + PG8_SB(b, h) + boff + n * 2048 + k * 1024); } while (0)
; #define PG8_MMA(ai, bj, At, Bt) do { __builtin_amdgcn_s_setprio(1); _Pragma("unroll") for (int m = 0; m < 4; ++m) _Pragma("unroll") for (int n = 0; n < 2; ++n) _Pragma("unroll") for (int k = 0; k < 2; ++k) \
;         acc[ai][bj][m][n] = __builtin_amdgcn_mfma_f32_16x16x32_bf16(Bt[n][k], At[m][k], acc[ai][bj][m][n], 0, 0, 0); __builtin_amdgcn_s_setprio(0); } while (0)
; #define PG8_WAIT_V(n) asm volatile("s_waitcnt vmcnt(" #n ")" ::: "memory")
; #define PG8_WAIT_L(n) asm volatile("s_waitcnt lgkmcnt(" #n ")" ::: "memory")
; #define PG8_BAR __builtin_amdgcn_s_barrier()
; #define PG8_SCHED __builtin_amdgcn_sched_barrier(0)
; template <class Epi, class Sched, bool ALIGN_EPI = false, bool SP2 = false>
; __device__ __forceinline__ void gemm_phase(PG8_LAS unsigned char* lds, const Gemm g, const Sched& S, const Epi& E) {
;     ...
;             PG8_WAIT_V(8); PG8_WAIT_L(0); PG8_BAR; PG8_MMA(1, 0, At, B0); PG8_MMA(1, 1, At, B1); PG8_BAR; PG8_SCHED;
;             PG8_LDB(B0, 1, 0); PG8_LDB(B1, 1, 1); PG8_SCHED; PG8_LDA(At, 1, 0); PG8_STAGE(PG8_SA(0, 1), a2 + hstep, voffA);
;             PG8_WAIT_V(8); PG8_WAIT_L(0); PG8_BAR; PG8_MMA(0, 0, At, B0); PG8_MMA(0, 1, At, B1); PG8_BAR; PG8_SCHED;
	s_setprio 1
	s_waitcnt lgkmcnt(0)
	v_mfma_f32_16x16x32_bf16 v[108:111], v[144:147], v[178:181], v[108:111]
	v_mfma_f32_16x16x32_bf16 v[108:111], v[148:151], v[198:201], v[108:111]
	v_mfma_f32_16x16x32_bf16 v[96:99], v[160:163], v[178:181], v[96:99]
	v_mfma_f32_16x16x32_bf16 v[96:99], v[166:169], v[198:201], v[96:99]
	v_mfma_f32_16x16x32_bf16 v[112:115], v[152:155], v[178:181], v[112:115]
	v_mfma_f32_16x16x32_bf16 v[112:115], v[156:159], v[198:201], v[112:115]
	v_mfma_f32_16x16x32_bf16 v[44:47], v[170:173], v[178:181], v[44:47]
	v_mfma_f32_16x16x32_bf16 v[44:47], v[174:177], v[198:201], v[44:47]
	v_mfma_f32_16x16x32_bf16 v[88:91], v[144:147], v[202:205], v[88:91]
	v_mfma_f32_16x16x32_bf16 v[88:91], v[148:151], v[220:223], v[88:91]
	v_mfma_f32_16x16x32_bf16 v[84:87], v[160:163], v[202:205], v[84:87]
	v_mfma_f32_16x16x32_bf16 v[84:87], v[166:169], v[220:223], v[84:87]
	v_mfma_f32_16x16x32_bf16 v[92:95], v[152:155], v[202:205], v[92:95]
	v_mfma_f32_16x16x32_bf16 v[92:95], v[156:159], v[220:223], v[92:95]
	v_mfma_f32_16x16x32_bf16 v[72:75], v[170:173], v[202:205], v[72:75]
	v_mfma_f32_16x16x32_bf16 v[72:75], v[174:177], v[220:223], v[72:75]
	s_setprio 0
	s_setprio 1
	v_mfma_f32_16x16x32_bf16 v[60:63], v[144:147], v[224:227], v[60:63]
	v_mfma_f32_16x16x32_bf16 v[60:63], v[148:151], v[228:231], v[60:63]
	v_mfma_f32_16x16x32_bf16 v[56:59], v[160:163], v[224:227], v[56:59]
	v_mfma_f32_16x16x32_bf16 v[56:59], v[166:169], v[228:231], v[56:59]
	v_mfma_f32_16x16x32_bf16 v[64:67], v[152:155], v[224:227], v[64:67]
	v_mfma_f32_16x16x32_bf16 v[64:67], v[156:159], v[228:231], v[64:67]
	v_mfma_f32_16x16x32_bf16 v[52:55], v[170:173], v[224:227], v[52:55]
	v_mfma_f32_16x16x32_bf16 v[52:55], v[174:177], v[228:231], v[52:55]
	v_mfma_f32_16x16x32_bf16 v[36:39], v[144:147], v[232:235], v[36:39]
	v_mfma_f32_16x16x32_bf16 v[36:39], v[148:151], v[236:239], v[36:39]
	v_mfma_f32_16x16x32_bf16 v[28:31], v[160:163], v[232:235], v[28:31]
	v_mfma_f32_16x16x32_bf16 v[28:31], v[166:169], v[236:239], v[28:31]
	v_mfma_f32_16x16x32_bf16 v[40:43], v[152:155], v[232:235], v[40:43]
	v_mfma_f32_16x16x32_bf16 v[40:43], v[156:159], v[236:239], v[40:43]
	v_mfma_f32_16x16x32_bf16 v[20:23], v[170:173], v[232:235], v[20:23]
	v_mfma_f32_16x16x32_bf16 v[20:23], v[174:177], v[236:239], v[20:23]
	s_setprio 0
	s_barrier
	s_add_i32 s57, 0, 0x18000
	s_add_i32 s58, 0, 0x1c000
	v_add_u32_e32 v156, s57, v1
	v_add_u32_e32 v174, s58, v1
	ds_read_b128 v[144:147], v156
	ds_read_b128 v[148:151], v156 offset:1024
	ds_read_b128 v[152:155], v156 offset:2048
	ds_read_b128 v[156:159], v156 offset:3072
	ds_read_b128 v[160:163], v174
	ds_read_b128 v[166:169], v174 offset:1024
	ds_read_b128 v[170:173], v174 offset:2048
	ds_read_b128 v[174:177], v174 offset:3072
	s_add_u32 s22, s22, s33
	s_addc_u32 s23, s23, 0
	s_mov_b32 m0, s47
	v_lshl_add_u64 v[244:245], s[22:23], 0, v[2:3]
	ds_read_b128 v[178:181], v143 offset:32768
	ds_read_b128 v[198:201], v143 offset:33792
	ds_read_b128 v[202:205], v143 offset:34816
	ds_read_b128 v[220:223], v143 offset:35840
	ds_read_b128 v[224:227], v143 offset:36864
	ds_read_b128 v[228:231], v143 offset:37888
	ds_read_b128 v[232:235], v143 offset:38912
	ds_read_b128 v[236:239], v143 offset:39936
	global_load_lds_dwordx4 v[244:245], off
	v_lshl_add_u64 v[244:245], s[22:23], 0, v[132:133]
	s_mov_b32 m0, s48
	s_nop 0
	global_load_lds_dwordx4 v[244:245], off
	s_waitcnt vmcnt(8)
	s_waitcnt lgkmcnt(0)
	s_barrier
	s_setprio 1
	s_waitcnt lgkmcnt(0)
	v_mfma_f32_16x16x32_bf16 v[100:103], v[144:147], v[178:181], v[100:103]
	v_mfma_f32_16x16x32_bf16 v[100:103], v[148:151], v[198:201], v[100:103]
	v_mfma_f32_16x16x32_bf16 v[16:19], v[160:163], v[178:181], v[16:19]
	v_mfma_f32_16x16x32_bf16 v[16:19], v[166:169], v[198:201], v[16:19]
	v_mfma_f32_16x16x32_bf16 v[68:71], v[152:155], v[178:181], v[68:71]
	v_mfma_f32_16x16x32_bf16 v[68:71], v[156:159], v[198:201], v[68:71]
	v_mfma_f32_16x16x32_bf16 v[4:7], v[170:173], v[178:181], v[4:7]
	v_mfma_f32_16x16x32_bf16 v[4:7], v[174:177], v[198:201], v[4:7]
	v_mfma_f32_16x16x32_bf16 v[116:119], v[144:147], v[202:205], v[116:119]
	v_mfma_f32_16x16x32_bf16 v[116:119], v[148:151], v[220:223], v[116:119]
	v_mfma_f32_16x16x32_bf16 v[32:35], v[160:163], v[202:205], v[32:35]
	v_mfma_f32_16x16x32_bf16 v[32:35], v[166:169], v[220:223], v[32:35]
	v_mfma_f32_16x16x32_bf16 v[80:83], v[152:155], v[202:205], v[80:83]
	v_mfma_f32_16x16x32_bf16 v[80:83], v[156:159], v[220:223], v[80:83]
	v_mfma_f32_16x16x32_bf16 v[8:11], v[170:173], v[202:205], v[8:11]
	v_mfma_f32_16x16x32_bf16 v[8:11], v[174:177], v[220:223], v[8:11]
	s_setprio 0
	s_setprio 1
	v_mfma_f32_16x16x32_bf16 v[124:127], v[144:147], v[224:227], v[124:127]
	v_mfma_f32_16x16x32_bf16 v[124:127], v[148:151], v[228:231], v[124:127]
	v_mfma_f32_16x16x32_bf16 v[48:51], v[160:163], v[224:227], v[48:51]
	v_mfma_f32_16x16x32_bf16 v[48:51], v[166:169], v[228:231], v[48:51]
	v_mfma_f32_16x16x32_bf16 v[104:107], v[152:155], v[224:227], v[104:107]
	v_mfma_f32_16x16x32_bf16 v[104:107], v[156:159], v[228:231], v[104:107]
	v_mfma_f32_16x16x32_bf16 v[12:15], v[170:173], v[224:227], v[12:15]
	v_mfma_f32_16x16x32_bf16 v[12:15], v[174:177], v[228:231], v[12:15]
	v_mfma_f32_16x16x32_bf16 v[128:131], v[144:147], v[232:235], v[128:131]
	v_mfma_f32_16x16x32_bf16 v[128:131], v[148:151], v[236:239], v[128:131]
	v_mfma_f32_16x16x32_bf16 v[76:79], v[160:163], v[232:235], v[76:79]
	v_mfma_f32_16x16x32_bf16 v[76:79], v[166:169], v[236:239], v[76:79]
	v_mfma_f32_16x16x32_bf16 v[120:123], v[152:155], v[232:235], v[120:123]
	v_mfma_f32_16x16x32_bf16 v[120:123], v[156:159], v[236:239], v[120:123]
	v_mfma_f32_16x16x32_bf16 v[24:27], v[170:173], v[232:235], v[24:27]
	v_mfma_f32_16x16x32_bf16 v[24:27], v[174:177], v[236:239], v[24:27]
	s_setprio 0
	s_barrier
; #define PG8_STAGE(bufoff, gbase, voff) do { _Pragma("unroll") for (int _i = 0; _i < 2; ++_i) \
;         __builtin_amdgcn_global_load_lds((const unsigned*)((const char*)(gbase) + (voff)[_i]), (PG8_LAS unsigned*)(lds + (bufoff) + ldsw + _i * 8192), 16, 0, 0); } while (0)
; #define PG8_LDA(dst, b, h) do { _Pragma("unroll") for (int m = 0; m < 4; ++m) _Pragma("unroll") for (int k = 0; k < 2; ++k) dst[m][k] = *(const PG8_LAS bf16x8*)(lds + PG8_SA(b, h) + aoff + m * 2048 + k * 1024); } while (0)
; #define PG8_MMA(ai, bj, At, Bt) do { __builtin_amdgcn_s_setprio(1); _Pragma("unroll") for (int m = 0; m < 4; ++m) _Pragma("unroll") for (int n = 0; n < 2; ++n) _Pragma("unroll") for (int k = 0; k < 2; ++k) \
;         acc[ai][bj][m][n] = __builtin_amdgcn_mfma_f32_16x16x32_bf16(Bt[n][k], At[m][k], acc[ai][bj][m][n], 0, 0, 0); __builtin_amdgcn_s_setprio(0); } while (0)
; #define PG8_WAIT_V(n) asm volatile("s_waitcnt vmcnt(" #n ")" ::: "memory")
; #define PG8_WAIT_L(n) asm volatile("s_waitcnt lgkmcnt(" #n ")" ::: "memory")
; #define PG8_BAR __builtin_amdgcn_s_barrier()
; #define PG8_SCHED __builtin_amdgcn_sched_barrier(0)
; template <class Epi, class Sched, bool ALIGN_EPI = false, bool SP2 = false>
; __device__ __forceinline__ void gemm_phase(PG8_LAS unsigned char* lds, const Gemm g, const Sched& S, const Epi& E) {
;     ...
;             PG8_LDA(At, 1, 1); PG8_STAGE(PG8_SB(1, 0), b3, voffB); PG8_STAGE(PG8_SB(1, 1), b3 + hstep, voffB); PG8_STAGE(PG8_SA(1, 0), a3, voffA);
;             PG8_WAIT_V(8); PG8_WAIT_L(0); PG8_BAR; PG8_MMA(1, 0, At, B0); PG8_MMA(1, 1, At, B1); PG8_BAR; PG8_SCHED;
;     ...
;         if (!has_next) break;
; #pragma unroll
;         for (int a = 0; a < 2; ++a)
; #pragma unroll
;             for (int b = 0; b < 2; ++b)
; #pragma unroll
;                 for (int m = 0; m < 4; ++m)
; #pragma unroll
;                     for (int n = 0; n < 2; ++n) acc[a][b][m][n] = (f32x4){0.f, 0.f, 0.f, 0.f};
;         cur = nxt; cA = nA; cB = nB; ++ui;
	s_add_i32 s22, s57, s13
	v_lshl_add_u64 v[184:185], v[184:185], 0, s[34:35]
	s_mov_b32 m0, s22
	ds_read_b128 v[178:181], v143 offset:49152
	ds_read_b128 v[198:201], v143 offset:50176
	ds_read_b128 v[202:205], v143 offset:51200
	ds_read_b128 v[220:223], v143 offset:52224
	ds_read_b128 v[224:227], v143 offset:53248
	ds_read_b128 v[228:231], v143 offset:54272
	ds_read_b128 v[232:235], v143 offset:55296
	ds_read_b128 v[236:239], v143 offset:56320
	global_load_lds_dwordx4 v[184:185], off
	v_lshl_add_u64 v[184:185], v[186:187], 0, s[34:35]
	s_add_i32 m0, s22, 0x2000
	s_add_i32 s22, s58, s13
	global_load_lds_dwordx4 v[184:185], off
	v_lshl_add_u64 v[184:185], v[196:197], 0, s[34:35]
	s_mov_b32 m0, s22
	s_nop 0
	global_load_lds_dwordx4 v[184:185], off
	v_lshl_add_u64 v[184:185], v[206:207], 0, s[34:35]
	s_add_i32 m0, s22, 0x2000
	s_nop 0
	global_load_lds_dwordx4 v[184:185], off
	v_lshl_add_u64 v[184:185], v[240:241], 0, s[34:35]
	s_mov_b32 m0, s50
	s_nop 0
	global_load_lds_dwordx4 v[184:185], off
	v_lshl_add_u64 v[184:185], v[242:243], 0, s[34:35]
	s_mov_b32 m0, s51
	s_nop 0
	global_load_lds_dwordx4 v[184:185], off
	s_waitcnt vmcnt(8)
	s_waitcnt lgkmcnt(0)
	s_barrier
	s_setprio 1
	s_waitcnt lgkmcnt(0)
	v_mfma_f32_16x16x32_bf16 v[108:111], v[144:147], v[178:181], v[108:111]
	v_mfma_f32_16x16x32_bf16 v[108:111], v[148:151], v[198:201], v[108:111]
	v_mfma_f32_16x16x32_bf16 v[96:99], v[160:163], v[178:181], v[96:99]
	v_mfma_f32_16x16x32_bf16 v[96:99], v[166:169], v[198:201], v[96:99]
	v_mfma_f32_16x16x32_bf16 v[112:115], v[152:155], v[178:181], v[112:115]
	v_mfma_f32_16x16x32_bf16 v[112:115], v[156:159], v[198:201], v[112:115]
	v_mfma_f32_16x16x32_bf16 v[44:47], v[170:173], v[178:181], v[44:47]
	v_mfma_f32_16x16x32_bf16 v[44:47], v[174:177], v[198:201], v[44:47]
	v_mfma_f32_16x16x32_bf16 v[88:91], v[144:147], v[202:205], v[88:91]
	v_mfma_f32_16x16x32_bf16 v[88:91], v[148:151], v[220:223], v[88:91]
	v_mfma_f32_16x16x32_bf16 v[84:87], v[160:163], v[202:205], v[84:87]
	v_mfma_f32_16x16x32_bf16 v[84:87], v[166:169], v[220:223], v[84:87]
	v_mfma_f32_16x16x32_bf16 v[92:95], v[152:155], v[202:205], v[92:95]
	v_mfma_f32_16x16x32_bf16 v[92:95], v[156:159], v[220:223], v[92:95]
	v_mfma_f32_16x16x32_bf16 v[72:75], v[170:173], v[202:205], v[72:75]
	v_mfma_f32_16x16x32_bf16 v[72:75], v[174:177], v[220:223], v[72:75]
	s_setprio 0
	s_setprio 1
	v_mfma_f32_16x16x32_bf16 v[60:63], v[144:147], v[224:227], v[60:63]
	v_mfma_f32_16x16x32_bf16 v[60:63], v[148:151], v[228:231], v[60:63]
	v_mfma_f32_16x16x32_bf16 v[56:59], v[160:163], v[224:227], v[56:59]
	v_mfma_f32_16x16x32_bf16 v[56:59], v[166:169], v[228:231], v[56:59]
	v_mfma_f32_16x16x32_bf16 v[64:67], v[152:155], v[224:227], v[64:67]
	v_mfma_f32_16x16x32_bf16 v[64:67], v[156:159], v[228:231], v[64:67]
	v_mfma_f32_16x16x32_bf16 v[52:55], v[170:173], v[224:227], v[52:55]
	v_mfma_f32_16x16x32_bf16 v[52:55], v[174:177], v[228:231], v[52:55]
	v_mfma_f32_16x16x32_bf16 v[36:39], v[144:147], v[232:235], v[36:39]
	v_mfma_f32_16x16x32_bf16 v[36:39], v[148:151], v[236:239], v[36:39]
	v_mfma_f32_16x16x32_bf16 v[28:31], v[160:163], v[232:235], v[28:31]
	v_mfma_f32_16x16x32_bf16 v[28:31], v[166:169], v[236:239], v[28:31]
	v_mfma_f32_16x16x32_bf16 v[40:43], v[152:155], v[232:235], v[40:43]
	v_mfma_f32_16x16x32_bf16 v[40:43], v[156:159], v[236:239], v[40:43]
	v_mfma_f32_16x16x32_bf16 v[20:23], v[170:173], v[232:235], v[20:23]
	v_mfma_f32_16x16x32_bf16 v[20:23], v[174:177], v[236:239], v[20:23]
	s_setprio 0
	s_barrier
	s_add_u32 s20, s20, 0x100
	s_addc_u32 s21, s21, 0
	v_lshl_add_u64 v[140:141], v[140:141], 0, s[62:63]
	v_lshl_add_u64 v[138:139], v[138:139], 0, s[62:63]
	s_cmp_ge_u32 s56, s29
	s_mov_b32 s22, s56
	s_cbranch_scc0 .LBB11_1896
	s_and_b64 vcc, exec, s[38:39]
	s_cbranch_vccnz .LBB11_1884
	v_mov_b32_e32 v20, 0
	s_mov_b32 s42, s53
	s_mov_b32 s28, s54
	s_mov_b64 s[14:15], s[18:19]
	s_mov_b64 s[16:17], s[4:5]
	s_mov_b32 s52, s55
	v_mov_b32_e32 v21, v20
	v_mov_b32_e32 v22, v20
	v_mov_b32_e32 v23, v20
	v_mov_b32_e32 v28, v20
	v_mov_b32_e32 v29, v20
	v_mov_b32_e32 v30, v20
	v_mov_b32_e32 v31, v20
	v_mov_b32_e32 v52, v20
	v_mov_b32_e32 v53, v20
	v_mov_b32_e32 v54, v20
	v_mov_b32_e32 v55, v20
	v_mov_b32_e32 v56, v20
	v_mov_b32_e32 v57, v20
	v_mov_b32_e32 v58, v20
	v_mov_b32_e32 v59, v20
	v_mov_b32_e32 v72, v20
	v_mov_b32_e32 v73, v20
	v_mov_b32_e32 v74, v20
	v_mov_b32_e32 v75, v20
	v_mov_b32_e32 v84, v20
	v_mov_b32_e32 v85, v20
	v_mov_b32_e32 v86, v20
	v_mov_b32_e32 v87, v20
	v_mov_b32_e32 v44, v20
	v_mov_b32_e32 v45, v20
	v_mov_b32_e32 v46, v20
	v_mov_b32_e32 v47, v20
	v_mov_b32_e32 v96, v20
	v_mov_b32_e32 v97, v20
	v_mov_b32_e32 v98, v20
	v_mov_b32_e32 v99, v20
	v_mov_b32_e32 v40, v20
	v_mov_b32_e32 v41, v20
	v_mov_b32_e32 v42, v20
	v_mov_b32_e32 v43, v20
	v_mov_b32_e32 v36, v20
	v_mov_b32_e32 v37, v20
	v_mov_b32_e32 v38, v20
	v_mov_b32_e32 v39, v20
	v_mov_b32_e32 v64, v20
	v_mov_b32_e32 v65, v20
	v_mov_b32_e32 v66, v20
	v_mov_b32_e32 v67, v20
	v_mov_b32_e32 v60, v20
	v_mov_b32_e32 v61, v20
	v_mov_b32_e32 v62, v20
	v_mov_b32_e32 v63, v20
	v_mov_b32_e32 v92, v20
	v_mov_b32_e32 v93, v20
	v_mov_b32_e32 v94, v20
	v_mov_b32_e32 v95, v20
	v_mov_b32_e32 v88, v20
	v_mov_b32_e32 v89, v20
	v_mov_b32_e32 v90, v20
	v_mov_b32_e32 v91, v20
	v_mov_b32_e32 v112, v20
	v_mov_b32_e32 v113, v20
	v_mov_b32_e32 v114, v20
	v_mov_b32_e32 v115, v20
	v_mov_b32_e32 v108, v20
	v_mov_b32_e32 v109, v20
	v_mov_b32_e32 v110, v20
	v_mov_b32_e32 v111, v20
	v_mov_b32_e32 v24, v20
	v_mov_b32_e32 v25, v20
	v_mov_b32_e32 v26, v20
	v_mov_b32_e32 v27, v20
	v_mov_b32_e32 v76, v20
	v_mov_b32_e32 v77, v20
	v_mov_b32_e32 v78, v20
	v_mov_b32_e32 v79, v20
	v_mov_b32_e32 v12, v20
	v_mov_b32_e32 v13, v20
	v_mov_b32_e32 v14, v20
	v_mov_b32_e32 v15, v20
	v_mov_b32_e32 v48, v20
	v_mov_b32_e32 v49, v20
	v_mov_b32_e32 v50, v20
	v_mov_b32_e32 v51, v20
	v_mov_b32_e32 v8, v20
	v_mov_b32_e32 v9, v20
	v_mov_b32_e32 v10, v20
	v_mov_b32_e32 v11, v20
	v_mov_b32_e32 v32, v20
	v_mov_b32_e32 v33, v20
	v_mov_b32_e32 v34, v20
	v_mov_b32_e32 v35, v20
	v_mov_b32_e32 v4, v20
	v_mov_b32_e32 v5, v20
	v_mov_b32_e32 v6, v20
	v_mov_b32_e32 v7, v20
	v_mov_b32_e32 v16, v20
	v_mov_b32_e32 v17, v20
	v_mov_b32_e32 v18, v20
	v_mov_b32_e32 v19, v20
	v_mov_b32_e32 v120, v20
	v_mov_b32_e32 v121, v20
	v_mov_b32_e32 v122, v20
	v_mov_b32_e32 v123, v20
	v_mov_b32_e32 v128, v20
	v_mov_b32_e32 v129, v20
	v_mov_b32_e32 v130, v20
	v_mov_b32_e32 v131, v20
	v_mov_b32_e32 v104, v20
	v_mov_b32_e32 v105, v20
	v_mov_b32_e32 v106, v20
	v_mov_b32_e32 v107, v20
	v_mov_b32_e32 v124, v20
	v_mov_b32_e32 v125, v20
	v_mov_b32_e32 v126, v20
	v_mov_b32_e32 v127, v20
	v_mov_b32_e32 v80, v20
	v_mov_b32_e32 v81, v20
	v_mov_b32_e32 v82, v20
	v_mov_b32_e32 v83, v20
	v_mov_b32_e32 v116, v20
	v_mov_b32_e32 v117, v20
	v_mov_b32_e32 v118, v20
	v_mov_b32_e32 v119, v20
	v_mov_b32_e32 v68, v20
	v_mov_b32_e32 v69, v20
	v_mov_b32_e32 v70, v20
	v_mov_b32_e32 v71, v20
	v_mov_b32_e32 v100, v20
	v_mov_b32_e32 v101, v20
	v_mov_b32_e32 v102, v20
	v_mov_b32_e32 v103, v20
	s_branch .LBB11_1884
